# attention: V ring stored in natural tr-read key order so P fragments need no permlane32_swap (32 swaps removed); static prio 1 for waves 4-7 in attention
# speedup vs baseline: 1.0899x; 1.0163x over previous
; __device__ __forceinline__ void attn_unit(const bf16* __restrict__ proj, bf16* __restrict__ cat, int b, int h, int qb, float lam, float oscale, const float* __restrict__ subln, const float* __restrict__ cw, char* lds) {
;     ...
;   asm volatile("s_waitcnt vmcnt(0)" ::: "memory");
;   __syncthreads();
; __global__ void __launch_bounds__(NWAVES * 64, 2) fwd_megakernel(Args args) {
;     ...
;             for (int i = 0; ; ++i) { int bh, qb;
;                 if (G == 256) { if (i >= 4) break; bh = xcd * 4 + i; qb = jq; } else { const int u = bx + i * G; if (u >= 1024) break; bh = u >> 5; qb = u & 31; }
;                 att::attn_unit((const att::bf16*)PROJ, (att::bf16*)CAT, bh >> 3, bh & 7, qb, lam, oscale, subln + l * 128, conv_w + l * 3 * 1024, (char*)lds); }
.LBB0_207:
	s_setprio 0
	s_waitcnt vmcnt(0)
	s_add_i32 s30, s30, 1
	s_mov_b64 s[28:29], 0
	s_barrier

; __device__ __forceinline__ int v_rd_base(int lane) { return ((lane & 3) << 3) | (((lane >> 2) & 3) << 6) | (((lane >> 4) & 1) << 5) | (((lane >> 5) & 1) << 8); }
; #define WAIT_BAR(N) asm volatile("s_waitcnt vmcnt(" #N ") lgkmcnt(0)\n\ts_barrier" ::: "memory")
; __device__ __forceinline__ void attn_unit(const bf16* __restrict__ proj, bf16* __restrict__ cat, int b, int h, int qb, float lam, float oscale, const float* __restrict__ subln, const float* __restrict__ cw, char* lds) {
;   int tid_ = threadIdx.x; asm volatile("" : "+v"(tid_));
;   const int tid = tid_, wid = __builtin_amdgcn_readfirstlane(tid >> 6), lane = tid & 63, r32 = lane & 31, hi = lane >> 5, rg = wid & 3, mp = wid >> 2;
;   char* K_lds = lds; char* V_lds = lds + 3 * SHM_K;
;   float* ws = (float*)(lds + OFF_WS) + wid * 64; float* li_l = ws; float* al_l = ws + 32;
;   const long rowbase = (long)b * SEQ;
;   const bf16* Kh = proj + rowbase * LDP + 1024 + h * 128; const bf16* Vh = proj + rowbase * LDP + 2048 + h * 128;
;   float m_reg = -1e30f, l_reg = 0; f32x16 o[4] = {}; bf16x8 qr[4];
;   const bf16* Qw = proj + (rowbase + qb * QROWS + rg * 32 + r32) * LDP + (2 * h + mp) * 64 + hi * 8;
; #pragma unroll
;   for (int d0 = 0; d0 < 4; ++d0) qr[d0] = *reinterpret_cast<const bf16x8*>(Qw + d0 * 16);
;   const int cbase = mp * 128;
;   unsigned kofs[2], vofs[2];
; #pragma unroll
;   for (int i = 0; i < 2; ++i) { const int q = wid + 8 * i, p = 64 * q + lane;
;     const int krow = p >> 4, kc8 = (p & 15) ^ (krow & 15); kofs[i] = (unsigned)(krow * LDP + kc8 * 8) * 2u;
;     const int kk = (p >> 7) * 8 + ((p & 31) >> 2), c = ((p >> 5) & 3) * 32 + (p & 3) * 8, k = (kk & ~0xC) | ((kk & 4) << 1) | ((kk & 8) >> 1); vofs[i] = (unsigned)(k * LDP + c) * 2u; }
;   const unsigned lds0 = (unsigned)(uintptr_t)lds, kdst = lds0 + wid * 1024, vdst = lds0 + 3 * SHM_K + wid * 1024;
;     ...
;   const int vb0 = (int)(lds0 + 3 * SHM_K) + v_rd_base(lane);
;     ...
;   f32x16 pA0, pA1, pB0, pB1; float mnA, mnB, alA, alB; bf16x8 pa0, pa1, pa2, pa3; constexpr int NT = SEQ / KVBLK;
;   asm volatile("s_waitcnt vmcnt(0)" ::: "memory");
;   DMA_K(0, 0); DMA_V(0, 0); DMA_K(1, 1);
;   WAIT_BAR(2);
;   qkt(pA0, pA1, K_lds, qr, r32, hi, cbase); partialSM(pA0, pA1, m_reg, mnA, alA);
.LBB0_215:
	s_mov_b64 s[28:29], -1
	s_and_b64 vcc, exec, s[20:21]
	s_cbranch_vccz .LBB0_208
	v_mov_b32_e32 v8, v161
	s_ashr_i32 s46, s73, 3
	v_readfirstlane_b32 s31, v8
	s_and_b32 s71, s31, 0xffffffc0
	s_lshl_b32 s20, s71, 2
	s_ashr_i32 s29, s31, 6
	s_add_i32 s70, s20, 0
	s_ashr_i32 s47, s46, 31
	s_and_b32 s25, s29, 3
	s_ashr_i32 s24, s31, 8
	s_cmp_lg_u32 s24, 0
	s_cbranch_scc0 .Latt_noprio
	s_setprio 1
.Latt_noprio:
	s_add_i32 s70, s70, 0x18000
	s_lshl_b64 s[44:45], s[46:47], 12
	s_mul_i32 s21, s46, 0x3000000
	s_mul_hi_i32 s20, s46, 0x3000000
	s_add_u32 s46, s66, s21
	s_addc_u32 s47, s67, s20
	s_lshl_b32 s38, s38, 7
	s_and_b32 s38, s38, 0xf80
	s_or_b32 s38, s44, s38
	s_lshl_b32 s39, s25, 5
	v_and_b32_e32 v174, 31, v8
	s_or_b32 s44, s38, s39
	v_or_b32_e32 v2, s44, v174
	v_mov_b64_e32 v[0:1], s[66:67]
	s_lshl_b32 s28, s73, 7
	v_mad_u64_u32 v[0:1], s[38:39], v2, s1, v[0:1]
	s_and_b32 s28, s28, 0x380
	s_lshl_b32 s38, s24, 6
	s_add_i32 s38, s38, s28
	v_bfe_u32 v179, v8, 5, 1
	v_mad_i32_i24 v1, s45, v200, v1
	s_ashr_i32 s39, s38, 31
	v_lshl_add_u64 v[0:1], s[38:39], 1, v[0:1]
	v_lshlrev_b32_e32 v162, 4, v179
	v_lshl_add_u64 v[0:1], v[0:1], 0, v[162:163]
	global_load_dwordx4 v[140:143], v[0:1], off
	global_load_dwordx4 v[136:139], v[0:1], off offset:32
	global_load_dwordx4 v[132:135], v[0:1], off offset:64
	global_load_dwordx4 v[128:131], v[0:1], off offset:96
	s_lshl_b32 s38, s28, 1
	s_add_u32 s75, s46, s38
	v_mov_b32_e32 v2, s31
	s_movk_i32 s38, 0xffc0
	s_addc_u32 s77, s47, 0
	v_bfi_b32 v2, s38, v2, v8
	s_add_u32 s46, s75, 0x1000
	v_ashrrev_i32_e32 v2, 4, v2
	s_addc_u32 s47, s77, 0
	v_xor_b32_e32 v3, v2, v8
	s_ashr_i32 s38, s71, 4
	v_mul_lo_u32 v2, v2, s33
	v_lshlrev_b32_e32 v3, 3, v3
	s_and_b32 s39, s38, 0x1ffff0
	s_lshr_b32 s38, s38, 1
	v_and_b32_e32 v177, 63, v8
	v_bfe_u32 v0, v8, 2, 3
	v_lshrrev_b32_e32 v180, 1, v8
	v_and_or_b32 v2, v3, s0, v2
	s_and_b32 s38, s38, 4
	v_lshlrev_b32_e32 v184, 1, v2
	v_bitop3_b32 v2, s71, v201, v177 bitop3:0xc8
	s_lshr_b32 s38, s71, 7
	s_lshl_b32 s38, s38, 3
	s_addk_i32 s71, 0x200
	v_lshlrev_b32_e32 v178, 3, v8
	v_or_b32_e32 v3, s38, v0
	s_ashr_i32 s38, s71, 4
	v_and_b32_e32 v1, 24, v178
	v_mul_u32_u24_e32 v3, 0x1800, v3
	s_and_b32 s39, s38, 0x1ffff0
	s_lshr_b32 s38, s38, 1
	v_or3_b32 v2, v3, v2, v1
	s_and_b32 s38, s38, 4
	v_lshlrev_b32_e32 v185, 1, v2
	v_or_b32_e32 v2, s71, v177
	s_lshr_b32 s38, s71, 7
	s_lshl_b32 s38, s38, 3
	v_ashrrev_i32_e32 v2, 4, v2
	s_add_u32 s78, s75, 0x800
	v_xor_b32_e32 v3, v2, v8
	s_addc_u32 s79, s77, 0
	s_lshl_b32 s39, s24, 7
	s_lshl_b32 s72, s29, 10
	v_mul_lo_u32 v2, v2, s33
	v_lshlrev_b32_e32 v3, 3, v3
	s_cmp_lg_u32 0, -1
	v_and_or_b32 v2, v3, s0, v2
	v_or_b32_e32 v0, s38, v0
	s_cselect_b32 s38, 0, 0
	s_waitcnt vmcnt(0)
	v_lshlrev_b32_e32 v186, 1, v2
	v_bitop3_b32 v2, s71, v201, v177 bitop3:0xc8
	s_add_i32 s71, s72, s38
	s_mov_b32 s74, m0
	s_mov_b32 m0, s71
	s_nop 0
	global_load_lds_dwordx4 v184, s[78:79]
	s_mov_b32 m0, s74
	s_add_i32 s38, s38, 0xc000
	s_add_i32 s74, s71, 0x2000
	s_mov_b32 s76, m0
	s_mov_b32 m0, s74
	s_nop 0
	global_load_lds_dwordx4 v186, s[78:79]
	s_mov_b32 m0, s76
	v_mul_u32_u24_e32 v0, 0x1800, v0
	s_add_i32 s72, s72, s38
	s_mov_b32 s74, m0
	s_mov_b32 m0, s72
	s_nop 0
	global_load_lds_dwordx4 v185, s[46:47]
	s_mov_b32 m0, s74
	v_or3_b32 v0, v0, v2, v1
	s_add_i32 s74, s71, 0xe000
	v_lshlrev_b32_e32 v187, 1, v0
	v_lshlrev_b32_e32 v9, 4, v8
	s_mov_b32 s76, m0
	s_mov_b32 m0, s74
	s_nop 0
	global_load_lds_dwordx4 v187, s[46:47]
	s_mov_b32 m0, s76
	s_add_u32 s46, s75, 0xc0800
	s_addc_u32 s47, s77, 0
	s_add_i32 s74, s71, 0x4000
	s_mov_b32 s76, m0
	s_mov_b32 m0, s74
	s_nop 0
	global_load_lds_dwordx4 v184, s[46:47]
	s_mov_b32 m0, s76
	v_and_b32_e32 v10, 0xf0, v9
	s_add_i32 s74, s71, 0x6000
	s_mov_b32 s76, m0
	s_mov_b32 m0, s74
	s_nop 0
	global_load_lds_dwordx4 v186, s[46:47]
	s_mov_b32 m0, s76
	v_lshl_add_u32 v189, v174, 8, 0
	v_bitop3_b32 v210, s39, v10, v162 bitop3:0x36
	s_waitcnt vmcnt(2) lgkmcnt(0)
	s_barrier
	v_add_u32_e32 v188, v189, v210
	ds_read_b128 v[0:3], v188
	ds_read_b128 v[4:7], v188 offset:8192
	s_waitcnt vmcnt(3) lgkmcnt(1)
	v_mfma_f32_32x32x16_bf16 v[32:47], v[0:3], v[140:143], 0
	v_or_b32_e32 v11, s39, v162
	v_bitop3_b32 v212, v11, v10, 32 bitop3:0x36
	v_add_u32_e32 v211, v189, v212
	v_bitop3_b32 v214, v11, v10, 64 bitop3:0x36
	v_add_u32_e32 v213, v189, v214
	s_movk_i32 s39, 0x60
	v_lshlrev_b32_e32 v181, 3, v177
	s_waitcnt lgkmcnt(0)
	v_mfma_f32_32x32x16_bf16 v[16:31], v[4:7], v[140:143], 0
	ds_read_b128 v[0:3], v211
	ds_read_b128 v[4:7], v211 offset:8192
	v_bitop3_b32 v216, v11, v10, s39 bitop3:0x36
	v_add_u32_e32 v215, v189, v216
	ds_read_b128 v[48:51], v215 offset:8192
	v_readlane_b32 s80, v255, 8
	s_mov_b32 s8, s80
	v_readlane_b32 s81, v255, 9
	s_waitcnt vmcnt(2) lgkmcnt(2)
	v_mfma_f32_32x32x16_bf16 v[32:47], v[0:3], v[136:139], v[32:47]
	ds_read_b128 v[0:3], v213
	v_readlane_b32 s82, v255, 10
	v_readlane_b32 s83, v255, 11
	v_readlane_b32 s84, v255, 12
	v_readlane_b32 s85, v255, 13
	v_readlane_b32 s86, v255, 14
	v_readlane_b32 s87, v255, 15
	s_waitcnt lgkmcnt(2)
	v_mfma_f32_32x32x16_bf16 v[16:31], v[4:7], v[136:139], v[16:31]
	v_and_b32_e32 v4, 0xc0, v9
	v_and_or_b32 v9, v181, 24, v4
	v_lshlrev_b32_e32 v4, 1, v8
	v_and_b32_e32 v8, 32, v4
	ds_read_b128 v[4:7], v213 offset:8192
	v_readlane_b32 s88, v255, 16
	v_readlane_b32 s89, v255, 17
	s_waitcnt vmcnt(1) lgkmcnt(1)
	v_mfma_f32_32x32x16_bf16 v[32:47], v[0:3], v[132:135], v[32:47]
	ds_read_b128 v[0:3], v215
	v_readlane_b32 s90, v255, 18
	v_readlane_b32 s91, v255, 19
	v_readlane_b32 s92, v255, 20
	v_readlane_b32 s93, v255, 21
	v_readlane_b32 s94, v255, 22
	v_readlane_b32 s95, v255, 23
	s_waitcnt lgkmcnt(1)
; #define WAIT_BAR(N) asm volatile("s_waitcnt vmcnt(" #N ") lgkmcnt(0)\n\ts_barrier" ::: "memory")
; #define DMA_K(t, slot) do { const bf16* kb_ = Kh + (long)(t) * KVBLK * LDP; glds16(kb_, kofs[0], kdst + (slot) * SHM_K); glds16(kb_, kofs[1], kdst + (slot) * SHM_K + 8192); } while (0)
; #define DMA_V(t, slot) do { const bf16* vb_ = Vh + (long)(t) * KVBLK * LDP; glds16(vb_, vofs[0], vdst + (slot) * SHM_V); glds16(vb_, vofs[1], vdst + (slot) * SHM_V + 8192); } while (0)
; __device__ __forceinline__ void partialSM(f32x16& p0, f32x16& p1, float& m_reg, float& mn, float& alpha) {
;   float pmax = p0[0];
; #pragma unroll
;   for (int r = 1; r < 16; ++r) pmax = fmaxf(pmax, p0[r]);
; #pragma unroll
;   for (int r = 0; r < 16; ++r) pmax = fmaxf(pmax, p1[r]);
;   { auto rr = __builtin_amdgcn_permlane32_swap(__float_as_uint(pmax), __float_as_uint(pmax), false, false);
;     pmax = fmaxf(__uint_as_float(rr[0]), __uint_as_float(rr[1])); }
;   if (__builtin_expect(__all(pmax - m_reg <= THR), 1)) { mn = m_reg; alpha = 1.f; }
;   else { mn = fmaxf(m_reg, pmax); alpha = __builtin_amdgcn_exp2f(m_reg - mn); m_reg = mn; }
; #pragma unroll
;   for (int r = 0; r < 16; ++r) p0[r] = p0[r] - mn;
; #pragma unroll
;   for (int r = 0; r < 16; ++r) p1[r] = p1[r] - mn;
; #pragma unroll
;   for (int r = 0; r < 16; ++r) p0[r] = __builtin_amdgcn_exp2f(p0[r]);
; }
; __device__ __forceinline__ void attn_unit(const bf16* __restrict__ proj, bf16* __restrict__ cat, int b, int h, int qb, float lam, float oscale, const float* __restrict__ subln, const float* __restrict__ cw, char* lds) {
;     ...
;   qkt(pA0, pA1, K_lds, qr, r32, hi, cbase); partialSM(pA0, pA1, m_reg, mnA, alA);
; #pragma unroll
;   for (int r = 0; r < 16; ++r) pA1[r] = __builtin_amdgcn_exp2f(pA1[r]);
;   DMA_V(1, 1); DMA_K(2, 2);
;   WAIT_BAR(4);
;   int sj = 1;
	v_mfma_f32_32x32x16_bf16 v[16:31], v[4:7], v[132:135], v[16:31]
	v_writelane_b32 v255, s8, 8
	v_and_b32_e32 v12, 0x100, v181
	v_or3_b32 v183, v9, v8, v12
	v_writelane_b32 v255, s9, 9
	v_writelane_b32 v255, s10, 10
	v_writelane_b32 v255, s11, 11
	v_writelane_b32 v255, s12, 12
	s_waitcnt vmcnt(0) lgkmcnt(0)
	v_mfma_f32_32x32x16_bf16 v[32:47], v[0:3], v[128:131], v[32:47]
	v_writelane_b32 v255, s13, 13
	v_writelane_b32 v255, s14, 14
	v_writelane_b32 v255, s15, 15
	v_add_u32_e32 v217, s38, v183
	v_writelane_b32 v255, s16, 16
	v_writelane_b32 v255, s17, 17
	v_writelane_b32 v255, s18, 18
	v_mfma_f32_32x32x16_bf16 v[16:31], v[48:51], v[128:131], v[16:31]
	s_nop 3
	v_max_f32_e32 v48, v33, v33
	v_max_f32_e32 v49, v32, v32
	v_max_f32_e32 v48, v49, v48
	v_max3_f32 v48, v48, v34, v35
	v_max3_f32 v48, v48, v36, v37
	v_max3_f32 v48, v48, v38, v39
	v_max3_f32 v48, v48, v40, v41
	v_max3_f32 v48, v48, v42, v43
	v_max3_f32 v48, v48, v44, v45
	v_max3_f32 v48, v48, v46, v47
	v_max3_f32 v48, v48, v16, v17
	v_max3_f32 v48, v48, v18, v19
	v_max3_f32 v48, v48, v20, v21
	v_max3_f32 v48, v48, v22, v23
	v_max3_f32 v48, v48, v24, v25
	v_max3_f32 v48, v48, v26, v27
	v_max3_f32 v48, v48, v28, v29
	v_max3_f32 v48, v48, v30, v31
	v_mov_b32_e32 v49, v48
	s_nop 1
	v_permlane32_swap_b32_e32 v48, v49
	v_max_f32_e32 v49, v49, v49
	v_max_f32_e32 v48, v48, v48
	v_max_f32_e32 v48, v48, v49
	v_add_f32_e32 v49, 0x7149f2ca, v48
	v_cmp_ge_f32_e32 vcc, s6, v49
	s_cmp_eq_u64 vcc, exec
	s_cselect_b64 vcc, -1, 0
	s_add_u32 s38, s75, 0xc1000
	s_addc_u32 s39, s77, 0
	s_add_i32 s46, s71, 0x10000
	s_mov_b32 s47, m0
	s_mov_b32 m0, s46
	s_nop 0
	global_load_lds_dwordx4 v185, s[38:39]
	s_mov_b32 m0, s47
	s_add_i32 s46, s71, 0x12000
	s_mov_b32 s47, m0
	s_mov_b32 m0, s46
	s_nop 0
	global_load_lds_dwordx4 v187, s[38:39]
	s_mov_b32 m0, s47
	s_add_u32 s38, s75, 0x180800
	v_writelane_b32 v255, s19, 19
	v_max_f32_e32 v48, 0xf149f2ca, v48
	s_addc_u32 s39, s77, 0
	s_add_i32 s46, s71, 0x8000
	v_writelane_b32 v255, s20, 20
	v_cndmask_b32_e32 v218, v48, v202, vcc
	s_mov_b32 s47, m0
	s_mov_b32 m0, s46
	s_nop 0
	global_load_lds_dwordx4 v184, s[38:39]
	s_mov_b32 m0, s47
	s_add_i32 s46, s71, 0xa000
	v_writelane_b32 v255, s21, 21
	v_sub_f32_e32 v49, 0xf149f2ca, v48
	v_sub_f32_e32 v16, v16, v218
	s_mov_b32 s47, m0
	s_mov_b32 m0, s46
	s_nop 0
	global_load_lds_dwordx4 v186, s[38:39]
	s_mov_b32 m0, s47
	s_and_b32 s46, s73, 7
	v_writelane_b32 v255, s22, 22
	v_exp_f32_e32 v64, v16
	v_exp_f32_e32 v16, v49
	s_lshl_b32 s46, s46, 8
	s_mov_b32 s81, s80
	v_writelane_b32 v255, s23, 23
	v_sub_f32_e32 v32, v32, v218
	v_sub_f32_e32 v33, v33, v218
	v_sub_f32_e32 v34, v34, v218
	v_sub_f32_e32 v35, v35, v218
	v_sub_f32_e32 v36, v36, v218
	v_sub_f32_e32 v37, v37, v218
	v_sub_f32_e32 v38, v38, v218
	v_sub_f32_e32 v39, v39, v218
	v_sub_f32_e32 v40, v40, v218
	v_sub_f32_e32 v41, v41, v218
	v_sub_f32_e32 v42, v42, v218
	v_sub_f32_e32 v43, v43, v218
	v_sub_f32_e32 v44, v44, v218
	v_sub_f32_e32 v45, v45, v218
	v_sub_f32_e32 v46, v46, v218
	v_sub_f32_e32 v47, v47, v218
	v_sub_f32_e32 v17, v17, v218
	v_sub_f32_e32 v18, v18, v218
	v_sub_f32_e32 v19, v19, v218
	v_sub_f32_e32 v20, v20, v218
	v_sub_f32_e32 v21, v21, v218
	v_sub_f32_e32 v22, v22, v218
	v_sub_f32_e32 v23, v23, v218
	v_sub_f32_e32 v24, v24, v218
	v_sub_f32_e32 v25, v25, v218
	v_sub_f32_e32 v26, v26, v218
	v_sub_f32_e32 v27, v27, v218
	v_sub_f32_e32 v28, v28, v218
	v_sub_f32_e32 v29, v29, v218
	v_sub_f32_e32 v30, v30, v218
	v_sub_f32_e32 v31, v31, v218
	s_or_b32 s21, s21, s46
	s_mov_b32 s82, s80
	s_mov_b32 s83, s80
	s_mov_b32 s84, s80
	s_mov_b32 s85, s80
	s_mov_b32 s86, s80
	s_mov_b32 s87, s80
	s_mov_b32 s88, s80
	s_mov_b32 s89, s80
	s_mov_b32 s90, s80
	s_mov_b32 s91, s80
	s_mov_b32 s92, s80
	s_mov_b32 s93, s80
	s_mov_b32 s94, s80
	s_mov_b32 s95, s80
	v_mov_b64_e32 v[0:1], s[80:81]
	v_exp_f32_e32 v80, v32
	v_exp_f32_e32 v81, v33
	v_exp_f32_e32 v82, v34
	v_exp_f32_e32 v83, v35
	v_exp_f32_e32 v84, v36
	v_exp_f32_e32 v85, v37
	v_exp_f32_e32 v86, v38
	v_exp_f32_e32 v87, v39
	v_exp_f32_e32 v88, v40
	v_exp_f32_e32 v89, v41
	v_exp_f32_e32 v90, v42
	v_exp_f32_e32 v91, v43
	v_exp_f32_e32 v92, v44
	v_exp_f32_e32 v93, v45
	v_exp_f32_e32 v94, v46
	v_exp_f32_e32 v95, v47
	v_exp_f32_e32 v65, v17
	v_exp_f32_e32 v66, v18
	v_exp_f32_e32 v67, v19
	v_exp_f32_e32 v68, v20
	v_exp_f32_e32 v69, v21
	v_exp_f32_e32 v70, v22
	v_exp_f32_e32 v71, v23
	v_exp_f32_e32 v72, v24
	v_exp_f32_e32 v73, v25
	v_exp_f32_e32 v74, v26
	v_exp_f32_e32 v75, v27
	v_exp_f32_e32 v76, v28
	v_exp_f32_e32 v77, v29
	v_exp_f32_e32 v78, v30
	v_exp_f32_e32 v79, v31
	s_add_u32 s73, s3, s21
	v_mov_b64_e32 v[14:15], s[94:95]
	s_waitcnt vmcnt(4) lgkmcnt(0)
	s_barrier
	s_addc_u32 s74, s62, s20
	v_mov_b64_e32 v[2:3], s[82:83]
	v_mov_b64_e32 v[4:5], s[84:85]
	v_mov_b64_e32 v[6:7], s[86:87]
	v_mov_b64_e32 v[8:9], s[88:89]
	v_mov_b64_e32 v[10:11], s[90:91]
	v_mov_b64_e32 v[12:13], s[92:93]
	v_cndmask_b32_e64 v220, v16, 1.0, vcc
	s_add_u32 s82, s75, 0x240800
	v_mov_b64_e32 v[62:63], v[14:15]
	v_mov_b64_e32 v[46:47], v[14:15]
	v_mov_b64_e32 v[30:31], v[14:15]
	s_mov_b32 s76, 1
	v_cmp_gt_u32_e64 s[38:39], 32, v177
	v_lshl_add_u32 v182, v174, 2, s70
	s_addc_u32 s83, s77, 0
	v_mov_b32_e32 v219, 0
	v_mov_b64_e32 v[60:61], v[12:13]
	v_mov_b64_e32 v[58:59], v[10:11]
	v_mov_b64_e32 v[56:57], v[8:9]
	v_mov_b64_e32 v[54:55], v[6:7]
	v_mov_b64_e32 v[52:53], v[4:5]
	v_mov_b64_e32 v[50:51], v[2:3]
	v_mov_b64_e32 v[48:49], v[0:1]
	v_mov_b64_e32 v[44:45], v[12:13]
	v_mov_b64_e32 v[42:43], v[10:11]
	v_mov_b64_e32 v[40:41], v[8:9]
	v_mov_b64_e32 v[38:39], v[6:7]
	v_mov_b64_e32 v[36:37], v[4:5]
	v_mov_b64_e32 v[34:35], v[2:3]
	v_mov_b64_e32 v[32:33], v[0:1]
	v_mov_b64_e32 v[28:29], v[12:13]
	v_mov_b64_e32 v[26:27], v[10:11]
	v_mov_b64_e32 v[24:25], v[8:9]
	v_mov_b64_e32 v[22:23], v[6:7]
	v_mov_b64_e32 v[20:21], v[4:5]
	v_mov_b64_e32 v[18:19], v[2:3]
	v_mov_b64_e32 v[16:17], v[0:1]
	s_mov_b32 s75, 1
	s_branch .LBB0_218

.LBB0_218:
	s_add_i32 s20, s76, 1
	s_cmp_lg_u32 s76, 2
	s_cselect_b32 s77, s20, 0
	s_lshl_b32 s46, s76, 14
	s_add_i32 s20, s46, 0xffffc000
	s_cmp_lg_u32 s76, 0
	s_cselect_b32 s47, s20, 0x8000
	s_add_i32 s20, s47, s71
	s_mov_b32 s21, m0
	s_mov_b32 m0, s20
	s_nop 0
	global_load_lds_dwordx4 v184, s[82:83]
	s_mov_b32 m0, s21
	s_addk_i32 s20, 0x2000
	s_add_u32 s79, s73, 0x800
	s_addc_u32 s81, s74, 0
	s_mov_b32 s21, m0
	s_mov_b32 m0, s20
	s_nop 0
	global_load_lds_dwordx4 v186, s[82:83]
	s_mov_b32 m0, s21
	s_add_u32 s20, s73, 0xc0800
	s_addc_u32 s21, s74, 0
	s_lshl_b32 s78, s77, 14
	s_add_i32 s76, s78, s72
	s_mov_b32 s84, m0
	s_mov_b32 m0, s76
	s_nop 0
	global_load_lds_dwordx4 v185, s[20:21]
	s_mov_b32 m0, s84
	s_addk_i32 s76, 0x2000
	s_mov_b32 s84, m0
	s_mov_b32 m0, s76
	s_nop 0
	global_load_lds_dwordx4 v187, s[20:21]
	s_mov_b32 m0, s84
	v_add_u32_e32 v104, s46, v189
	v_add_u32_e32 v100, v104, v210
	v_add_u32_e32 v105, v104, v212
	ds_read_b128 v[96:99], v100
	ds_read_b128 v[100:103], v100 offset:8192
	ds_read_b128 v[144:147], v105
	ds_read_b128 v[148:151], v105 offset:8192
	v_add_u32_e32 v105, v104, v214
	v_add_u32_e32 v104, v104, v216
	ds_read_b128 v[152:155], v105
	ds_read_b128 v[222:225], v105 offset:8192
	ds_read_b128 v[156:159], v104
	ds_read_b128 v[226:229], v104 offset:8192
	v_add_f32_e32 v104, 0, v80
	v_add_f32_e32 v104, v81, v104
	v_add_f32_e32 v104, v82, v104
	v_add_f32_e32 v104, v83, v104
	v_add_f32_e32 v104, v84, v104
	v_add_f32_e32 v104, v85, v104
	v_add_f32_e32 v104, v86, v104
	v_add_f32_e32 v104, v87, v104
	s_nop 0
	v_add_f32_e32 v104, v88, v104
	s_waitcnt lgkmcnt(7)
	v_mfma_f32_32x32x16_bf16 v[112:127], v[96:99], v[140:143], 0
	v_add_f32_e32 v104, v89, v104
	v_add_f32_e32 v104, v90, v104
	v_add_f32_e32 v104, v91, v104
	v_add_f32_e32 v104, v92, v104
	v_add_f32_e32 v104, v93, v104
	v_add_f32_e32 v104, v94, v104
	v_add_f32_e32 v104, v95, v104
	s_nop 0
	v_add_f32_e32 v96, v64, v104
	v_add_f32_e32 v96, v65, v96
	v_add_f32_e32 v96, v66, v96
	v_add_f32_e32 v96, v67, v96
	v_add_f32_e32 v96, v68, v96
	v_add_f32_e32 v96, v69, v96
	v_add_f32_e32 v96, v70, v96
	v_add_f32_e32 v196, v71, v96
	s_waitcnt lgkmcnt(6)
	v_mfma_f32_32x32x16_bf16 v[96:111], v[100:103], v[140:143], 0
	s_nop 0
	v_add_f32_e32 v196, v72, v196
	s_waitcnt lgkmcnt(5)
	v_mfma_f32_32x32x16_bf16 v[112:127], v[144:147], v[136:139], v[112:127]
	v_add_f32_e32 v196, v73, v196
	v_add_f32_e32 v196, v74, v196
	v_add_f32_e32 v196, v75, v196
	v_add_f32_e32 v196, v76, v196
	v_add_f32_e32 v196, v77, v196
	v_add_f32_e32 v196, v78, v196
	v_add_f32_e32 v196, v79, v196
	s_nop 0
	v_mov_b32_e32 v144, v196
	s_nop 1
	v_permlane32_swap_b32_e32 v196, v144
	v_add_f32_e32 v221, v196, v144
	v_cvt_pk_bf16_f32 v144, v80, v81
	v_cvt_pk_bf16_f32 v145, v82, v83
	v_cvt_pk_bf16_f32 v146, v84, v85
	v_cvt_pk_bf16_f32 v147, v86, v87
	v_fmac_f32_e32 v221, v219, v220
	v_cvt_pk_bf16_f32 v84, v88, v89
	v_cvt_pk_bf16_f32 v85, v90, v91
	v_cvt_pk_bf16_f32 v86, v92, v93
	v_cvt_pk_bf16_f32 v87, v94, v95
	v_cvt_pk_bf16_f32 v80, v64, v65
	v_cvt_pk_bf16_f32 v81, v66, v67
	v_cvt_pk_bf16_f32 v82, v68, v69
	v_cvt_pk_bf16_f32 v83, v70, v71
	v_cvt_pk_bf16_f32 v64, v72, v73
	v_cvt_pk_bf16_f32 v65, v74, v75
	v_cvt_pk_bf16_f32 v66, v76, v77
	v_cvt_pk_bf16_f32 v67, v78, v79
	s_waitcnt lgkmcnt(4)
	v_mfma_f32_32x32x16_bf16 v[96:111], v[148:151], v[136:139], v[96:111]
	v_add_u32_e32 v196, s47, v217
	s_waitcnt lgkmcnt(3)
	v_mfma_f32_32x32x16_bf16 v[112:127], v[152:155], v[132:135], v[112:127]
	ds_read_b64_tr_b16 v[72:73], v196
	ds_read_b64_tr_b16 v[88:89], v196 offset:512
	ds_read_b64_tr_b16 v[152:153], v196 offset:1024
	ds_read_b64_tr_b16 v[230:231], v196 offset:1536
	ds_read_b64_tr_b16 v[74:75], v196 offset:2048
	ds_read_b64_tr_b16 v[90:91], v196 offset:2560
	ds_read_b64_tr_b16 v[154:155], v196 offset:3072
	ds_read_b64_tr_b16 v[232:233], v196 offset:3584
	s_waitcnt lgkmcnt(10)
	v_mfma_f32_32x32x16_bf16 v[96:111], v[222:225], v[132:135], v[96:111]
	s_waitcnt lgkmcnt(9)
	v_mfma_f32_32x32x16_bf16 v[112:127], v[156:159], v[128:131], v[112:127]
	ds_read_b64_tr_b16 v[234:235], v196 offset:4096
	ds_read_b64_tr_b16 v[238:239], v196 offset:4608
	ds_read_b64_tr_b16 v[242:243], v196 offset:5120
	ds_read_b64_tr_b16 v[156:157], v196 offset:5632
	ds_read_b64_tr_b16 v[236:237], v196 offset:6144
	ds_read_b64_tr_b16 v[240:241], v196 offset:6656
	ds_read_b64_tr_b16 v[244:245], v196 offset:7168
	ds_read_b64_tr_b16 v[158:159], v196 offset:7680
	ds_read_b64_tr_b16 v[148:149], v196 offset:8192
	ds_read_b64_tr_b16 v[92:93], v196 offset:8704
	ds_read_b64_tr_b16 v[76:77], v196 offset:9216
	ds_read_b64_tr_b16 v[68:69], v196 offset:9728
	ds_read_b64_tr_b16 v[150:151], v196 offset:10240
	ds_read_b64_tr_b16 v[94:95], v196 offset:10752
	ds_read_b64_tr_b16 v[78:79], v196 offset:11264
	ds_read_b64_tr_b16 v[70:71], v196 offset:11776
	s_waitcnt lgkmcnt(14)
	v_mfma_f32_32x32x16_bf16 v[96:111], v[226:229], v[128:131], v[96:111]
	v_mfma_f32_32x32x16_bf16 v[0:15], v[144:147], v[72:75], v[0:15]
	v_max3_f32 v72, v112, v113, v114
	v_max3_f32 v72, v72, v115, v116
	v_max3_f32 v72, v72, v117, v118
	v_max3_f32 v72, v72, v119, v120
	v_mfma_f32_32x32x16_bf16 v[48:63], v[144:147], v[88:91], v[48:63]
	v_max3_f32 v72, v72, v121, v122
	v_max3_f32 v72, v72, v123, v124
	v_max3_f32 v72, v72, v125, v126
	s_nop 2
	v_max3_f32 v72, v72, v127, v96
	v_mfma_f32_32x32x16_bf16 v[32:47], v[144:147], v[152:155], v[32:47]
	v_max3_f32 v72, v72, v97, v98
	v_max3_f32 v72, v72, v99, v100
	v_max3_f32 v72, v72, v101, v102
	v_max3_f32 v72, v72, v103, v104
	v_mfma_f32_32x32x16_bf16 v[16:31], v[144:147], v[230:233], v[16:31]
	v_max_f32_e32 v72, v72, v72
	v_max_f32_e32 v73, v105, v105
	v_max_f32_e32 v72, v72, v73
	v_max3_f32 v72, v72, v106, v107
	v_max3_f32 v72, v72, v108, v109
	v_max3_f32 v197, v72, v110, v111
	ds_read_b64_tr_b16 v[152:153], v196 offset:12288
	ds_read_b64_tr_b16 v[144:145], v196 offset:12800
	ds_read_b64_tr_b16 v[88:89], v196 offset:13312
	ds_read_b64_tr_b16 v[72:73], v196 offset:13824
	ds_read_b64_tr_b16 v[154:155], v196 offset:14336
	ds_read_b64_tr_b16 v[146:147], v196 offset:14848
	ds_read_b64_tr_b16 v[90:91], v196 offset:15360
	ds_read_b64_tr_b16 v[74:75], v196 offset:15872
	v_mov_b32_e32 v196, v197
	s_nop 1
	v_permlane32_swap_b32_e32 v197, v196
	v_max_f32_e32 v196, v196, v196
	v_max_f32_e32 v197, v197, v197
	v_max_f32_e32 v196, v197, v196
	v_sub_f32_e32 v197, v196, v218
	v_cmp_ge_f32_e32 vcc, s6, v197
	s_cmp_eq_u64 vcc, exec
	v_max_f32_e32 v197, v218, v218
	s_waitcnt lgkmcnt(14)
	v_mfma_f32_32x32x16_bf16 v[0:15], v[84:87], v[234:237], v[0:15]
	s_cselect_b64 vcc, -1, 0
	v_max_f32_e32 v196, v197, v196
	v_cndmask_b32_e32 v220, v196, v218, vcc
	v_sub_f32_e32 v196, v218, v220
	v_exp_f32_e32 v196, v196
	s_nop 0
	v_cndmask_b32_e64 v218, v196, 1.0, vcc
	v_mov_b32_e32 v196, v220
	v_mfma_f32_32x32x16_bf16 v[48:63], v[84:87], v[238:241], v[48:63]
	v_sub_f32_e32 v113, v113, v196
	v_sub_f32_e32 v112, v112, v196
	v_add_f32_e64 v114, v114, -v196
	v_add_f32_e64 v115, v115, -v196
	v_add_f32_e64 v116, v116, -v196
	v_add_f32_e64 v117, v117, -v196
	v_pk_add_f32 v[118:119], v[118:119], v[196:197] op_sel_hi:[1,0] neg_lo:[0,1] neg_hi:[0,1]
	s_nop 0
	v_mfma_f32_32x32x16_bf16 v[32:47], v[84:87], v[242:245], v[32:47]
	v_add_f32_e64 v120, v120, -v196
	v_add_f32_e64 v121, v121, -v196
	v_add_f32_e64 v122, v122, -v196
	v_add_f32_e64 v123, v123, -v196
	v_add_f32_e64 v124, v124, -v196
	v_add_f32_e64 v125, v125, -v196
	v_pk_add_f32 v[126:127], v[126:127], v[196:197] op_sel_hi:[1,0] neg_lo:[0,1] neg_hi:[0,1]
	s_nop 0
	v_mfma_f32_32x32x16_bf16 v[16:31], v[84:87], v[156:159], v[16:31]
	v_sub_f32_e32 v97, v97, v196
	v_sub_f32_e32 v96, v96, v196
	v_add_f32_e64 v98, v98, -v196
	v_add_f32_e64 v99, v99, -v196
	v_add_f32_e64 v100, v100, -v196
	v_add_f32_e64 v101, v101, -v196
	v_pk_add_f32 v[102:103], v[102:103], v[196:197] op_sel_hi:[1,0] neg_lo:[0,1] neg_hi:[0,1]
	s_nop 0
	s_waitcnt lgkmcnt(11)
	v_mfma_f32_32x32x16_bf16 v[0:15], v[80:83], v[148:151], v[0:15]
	v_add_f32_e64 v104, v104, -v196
	v_add_f32_e64 v105, v105, -v196
	v_add_f32_e64 v106, v106, -v196
	v_add_f32_e64 v107, v107, -v196
	v_add_f32_e64 v108, v108, -v196
	v_add_f32_e64 v109, v109, -v196
	v_pk_add_f32 v[110:111], v[110:111], v[196:197] op_sel_hi:[1,0] neg_lo:[0,1] neg_hi:[0,1]
	s_nop 0
	s_waitcnt lgkmcnt(10)
	v_mfma_f32_32x32x16_bf16 v[48:63], v[80:83], v[92:95], v[48:63]
	v_exp_f32_e32 v112, v112
	v_exp_f32_e32 v113, v113
	v_exp_f32_e32 v114, v114
	v_exp_f32_e32 v115, v115
	s_waitcnt lgkmcnt(9)
	v_mfma_f32_32x32x16_bf16 v[32:47], v[80:83], v[76:79], v[32:47]
	v_exp_f32_e32 v116, v116
	v_exp_f32_e32 v117, v117
	v_exp_f32_e32 v118, v118
	v_exp_f32_e32 v119, v119
	s_waitcnt lgkmcnt(8)
	v_mfma_f32_32x32x16_bf16 v[16:31], v[80:83], v[68:71], v[16:31]
	v_exp_f32_e32 v120, v120
	v_exp_f32_e32 v121, v121
	v_exp_f32_e32 v122, v122
	v_exp_f32_e32 v123, v123
	s_waitcnt lgkmcnt(3)
	v_mfma_f32_32x32x16_bf16 v[0:15], v[64:67], v[152:155], v[0:15]
	v_exp_f32_e32 v124, v124
	v_exp_f32_e32 v125, v125
	v_exp_f32_e32 v126, v126
	v_exp_f32_e32 v127, v127
	s_waitcnt lgkmcnt(2)
	v_mfma_f32_32x32x16_bf16 v[48:63], v[64:67], v[144:147], v[48:63]
	v_exp_f32_e32 v96, v96
	v_exp_f32_e32 v97, v97
	v_exp_f32_e32 v98, v98
	v_exp_f32_e32 v99, v99
	v_exp_f32_e32 v100, v100
	s_waitcnt lgkmcnt(1)
	v_mfma_f32_32x32x16_bf16 v[32:47], v[64:67], v[88:91], v[32:47]
	v_exp_f32_e32 v101, v101
	v_exp_f32_e32 v102, v102
	v_exp_f32_e32 v103, v103
	v_exp_f32_e32 v104, v104
	v_exp_f32_e32 v105, v105
	s_waitcnt lgkmcnt(0)
	v_mfma_f32_32x32x16_bf16 v[16:31], v[64:67], v[72:75], v[16:31]
	v_exp_f32_e32 v106, v106
	v_exp_f32_e32 v107, v107
	v_exp_f32_e32 v108, v108
	v_exp_f32_e32 v109, v109
	v_exp_f32_e32 v110, v110
	v_exp_f32_e32 v111, v111
	v_cmp_gt_f32_e32 vcc, 1.0, v218
	s_cbranch_vccz .LBB0_222
	s_and_saveexec_b64 s[20:21], s[38:39]
	ds_write_b32 v182, v218 offset:128
	s_or_b64 exec, exec, s[20:21]
	s_waitcnt lgkmcnt(0)
	v_add_u32_e32 v76, s70, v162
	ds_read_b128 v[64:67], v76 offset:224
	ds_read_b128 v[68:71], v76 offset:192
	ds_read_b128 v[72:75], v76 offset:160
	ds_read_b128 v[76:79], v76 offset:128
	s_waitcnt lgkmcnt(3)
	v_pk_mul_f32 v[12:13], v[12:13], v[64:65]
	s_waitcnt lgkmcnt(2)
	v_pk_mul_f32 v[8:9], v[8:9], v[68:69]
	s_waitcnt lgkmcnt(1)
	v_pk_mul_f32 v[4:5], v[4:5], v[72:73]
	v_pk_mul_f32 v[14:15], v[14:15], v[66:67]
	v_pk_mul_f32 v[10:11], v[10:11], v[70:71]
	v_pk_mul_f32 v[6:7], v[6:7], v[74:75]
	s_waitcnt lgkmcnt(0)
	v_pk_mul_f32 v[2:3], v[2:3], v[78:79]
	v_pk_mul_f32 v[0:1], v[0:1], v[76:77]
	v_pk_mul_f32 v[60:61], v[60:61], v[64:65]
	v_pk_mul_f32 v[56:57], v[56:57], v[68:69]
	v_pk_mul_f32 v[52:53], v[52:53], v[72:73]
	v_pk_mul_f32 v[62:63], v[62:63], v[66:67]
	v_pk_mul_f32 v[58:59], v[58:59], v[70:71]
	v_pk_mul_f32 v[54:55], v[54:55], v[74:75]
	v_pk_mul_f32 v[50:51], v[50:51], v[78:79]
	v_pk_mul_f32 v[48:49], v[48:49], v[76:77]
	v_pk_mul_f32 v[44:45], v[44:45], v[64:65]
	v_pk_mul_f32 v[40:41], v[40:41], v[68:69]
	v_pk_mul_f32 v[36:37], v[36:37], v[72:73]
	v_pk_mul_f32 v[46:47], v[46:47], v[66:67]
	v_pk_mul_f32 v[42:43], v[42:43], v[70:71]
	v_pk_mul_f32 v[38:39], v[38:39], v[74:75]
	v_pk_mul_f32 v[34:35], v[34:35], v[78:79]
	v_pk_mul_f32 v[32:33], v[32:33], v[76:77]
	v_pk_mul_f32 v[28:29], v[28:29], v[64:65]
	v_pk_mul_f32 v[24:25], v[24:25], v[68:69]
	v_pk_mul_f32 v[20:21], v[20:21], v[72:73]
	v_pk_mul_f32 v[30:31], v[30:31], v[66:67]
	v_pk_mul_f32 v[26:27], v[26:27], v[70:71]
	v_pk_mul_f32 v[22:23], v[22:23], v[74:75]
	v_pk_mul_f32 v[18:19], v[18:19], v[78:79]
	v_pk_mul_f32 v[16:17], v[16:17], v[76:77]

.LBB0_226:
	s_add_i32 s20, s77, 1
	s_cmp_lg_u32 s77, 2
	s_cselect_b32 s76, s20, 0
	s_lshl_b32 s20, s76, 14
	s_add_i32 s46, s20, s72
	s_add_i32 s47, s46, 0x2000
	s_add_u32 s20, s79, 0x180000
	s_addc_u32 s21, s81, 0
	s_mov_b32 s77, m0
	s_mov_b32 m0, s46
	s_nop 0
	global_load_lds_dwordx4 v185, s[20:21]
	s_mov_b32 m0, s77
	s_mov_b32 s46, m0
	s_mov_b32 m0, s47
	s_nop 0
	global_load_lds_dwordx4 v187, s[20:21]
	s_mov_b32 m0, s46
	v_add_u32_e32 v72, s78, v189
	v_add_u32_e32 v68, v72, v210
	v_add_u32_e32 v73, v72, v212
	ds_read_b128 v[64:67], v68
	ds_read_b128 v[68:71], v68 offset:8192
	ds_read_b128 v[144:147], v73
	ds_read_b128 v[148:151], v73 offset:8192
	v_add_u32_e32 v73, v72, v214
	v_add_u32_e32 v72, v72, v216
	ds_read_b128 v[152:155], v73
	ds_read_b128 v[222:225], v73 offset:8192
	ds_read_b128 v[156:159], v72
	ds_read_b128 v[226:229], v72 offset:8192
	v_add_f32_e32 v72, 0, v112
	v_add_f32_e32 v72, v113, v72
	v_add_f32_e32 v72, v114, v72
	v_add_f32_e32 v72, v115, v72
	v_add_f32_e32 v72, v116, v72
	v_add_f32_e32 v72, v117, v72
	v_add_f32_e32 v72, v118, v72
	v_add_f32_e32 v72, v119, v72
	s_nop 0
	v_add_f32_e32 v72, v120, v72
	s_waitcnt lgkmcnt(7)
	v_mfma_f32_32x32x16_bf16 v[80:95], v[64:67], v[140:143], 0
	v_add_f32_e32 v72, v121, v72
	v_add_f32_e32 v72, v122, v72
	v_add_f32_e32 v72, v123, v72
	v_add_f32_e32 v72, v124, v72
	v_add_f32_e32 v72, v125, v72
	v_add_f32_e32 v72, v126, v72
	v_add_f32_e32 v72, v127, v72
	s_nop 0
	v_add_f32_e32 v64, v96, v72
	v_add_f32_e32 v64, v97, v64
	v_add_f32_e32 v64, v98, v64
	v_add_f32_e32 v64, v99, v64
	v_add_f32_e32 v64, v100, v64
	v_add_f32_e32 v64, v101, v64
	v_add_f32_e32 v64, v102, v64
	v_add_f32_e32 v196, v103, v64
	s_waitcnt lgkmcnt(6)
	v_mfma_f32_32x32x16_bf16 v[64:79], v[68:71], v[140:143], 0
	s_nop 0
	v_add_f32_e32 v196, v104, v196
	s_waitcnt lgkmcnt(5)
	v_mfma_f32_32x32x16_bf16 v[80:95], v[144:147], v[136:139], v[80:95]
	v_add_f32_e32 v196, v105, v196
	v_add_f32_e32 v196, v106, v196
	v_add_f32_e32 v196, v107, v196
	v_add_f32_e32 v196, v108, v196
	v_add_f32_e32 v196, v109, v196
	v_add_f32_e32 v196, v110, v196
	v_add_f32_e32 v196, v111, v196
	s_nop 0
	v_mov_b32_e32 v144, v196
	s_nop 1
	v_permlane32_swap_b32_e32 v196, v144
	v_add_f32_e32 v219, v196, v144
	v_cvt_pk_bf16_f32 v144, v112, v113
	v_cvt_pk_bf16_f32 v145, v114, v115
	v_cvt_pk_bf16_f32 v146, v116, v117
	v_cvt_pk_bf16_f32 v147, v118, v119
	v_fmac_f32_e32 v219, v221, v218
	v_cvt_pk_bf16_f32 v116, v120, v121
	v_cvt_pk_bf16_f32 v117, v122, v123
	v_cvt_pk_bf16_f32 v118, v124, v125
	v_cvt_pk_bf16_f32 v119, v126, v127
	v_cvt_pk_bf16_f32 v112, v96, v97
	v_cvt_pk_bf16_f32 v113, v98, v99
	v_cvt_pk_bf16_f32 v114, v100, v101
	v_cvt_pk_bf16_f32 v115, v102, v103
	v_cvt_pk_bf16_f32 v96, v104, v105
	v_cvt_pk_bf16_f32 v97, v106, v107
	v_cvt_pk_bf16_f32 v98, v108, v109
	v_cvt_pk_bf16_f32 v99, v110, v111
	s_waitcnt lgkmcnt(4)
	v_mfma_f32_32x32x16_bf16 v[64:79], v[148:151], v[136:139], v[64:79]
	v_add_u32_e32 v196, s86, v217
	s_waitcnt lgkmcnt(3)
	v_mfma_f32_32x32x16_bf16 v[80:95], v[152:155], v[132:135], v[80:95]
	ds_read_b64_tr_b16 v[104:105], v196
	ds_read_b64_tr_b16 v[120:121], v196 offset:512
	ds_read_b64_tr_b16 v[152:153], v196 offset:1024
	ds_read_b64_tr_b16 v[230:231], v196 offset:1536
	ds_read_b64_tr_b16 v[106:107], v196 offset:2048
	ds_read_b64_tr_b16 v[122:123], v196 offset:2560
	ds_read_b64_tr_b16 v[154:155], v196 offset:3072
	ds_read_b64_tr_b16 v[232:233], v196 offset:3584
	s_waitcnt lgkmcnt(10)
	v_mfma_f32_32x32x16_bf16 v[64:79], v[222:225], v[132:135], v[64:79]
	s_waitcnt lgkmcnt(9)
	v_mfma_f32_32x32x16_bf16 v[80:95], v[156:159], v[128:131], v[80:95]
	ds_read_b64_tr_b16 v[234:235], v196 offset:4096
	ds_read_b64_tr_b16 v[238:239], v196 offset:4608
	ds_read_b64_tr_b16 v[242:243], v196 offset:5120
	ds_read_b64_tr_b16 v[156:157], v196 offset:5632
	ds_read_b64_tr_b16 v[236:237], v196 offset:6144
	ds_read_b64_tr_b16 v[240:241], v196 offset:6656
	ds_read_b64_tr_b16 v[244:245], v196 offset:7168
	ds_read_b64_tr_b16 v[158:159], v196 offset:7680
	ds_read_b64_tr_b16 v[148:149], v196 offset:8192
	ds_read_b64_tr_b16 v[124:125], v196 offset:8704
	ds_read_b64_tr_b16 v[108:109], v196 offset:9216
	ds_read_b64_tr_b16 v[100:101], v196 offset:9728
	ds_read_b64_tr_b16 v[150:151], v196 offset:10240
	ds_read_b64_tr_b16 v[126:127], v196 offset:10752
	ds_read_b64_tr_b16 v[110:111], v196 offset:11264
	ds_read_b64_tr_b16 v[102:103], v196 offset:11776
	s_waitcnt lgkmcnt(14)
	v_mfma_f32_32x32x16_bf16 v[64:79], v[226:229], v[128:131], v[64:79]
	v_mfma_f32_32x32x16_bf16 v[0:15], v[144:147], v[104:107], v[0:15]
	v_max3_f32 v104, v80, v81, v82
	v_max3_f32 v104, v104, v83, v84
	v_max3_f32 v104, v104, v85, v86
	v_max3_f32 v104, v104, v87, v88
	v_mfma_f32_32x32x16_bf16 v[48:63], v[144:147], v[120:123], v[48:63]
	v_max3_f32 v104, v104, v89, v90
	v_max3_f32 v104, v104, v91, v92
	v_max3_f32 v104, v104, v93, v94
	s_nop 2
	v_max3_f32 v104, v104, v95, v64
	v_mfma_f32_32x32x16_bf16 v[32:47], v[144:147], v[152:155], v[32:47]
	v_max3_f32 v104, v104, v65, v66
	v_max3_f32 v104, v104, v67, v68
	v_max3_f32 v104, v104, v69, v70
	v_max3_f32 v104, v104, v71, v72
	v_mfma_f32_32x32x16_bf16 v[16:31], v[144:147], v[230:233], v[16:31]
	v_max_f32_e32 v104, v104, v104
	v_max_f32_e32 v105, v73, v73
	v_max_f32_e32 v104, v104, v105
	v_max3_f32 v104, v104, v74, v75
	v_max3_f32 v104, v104, v76, v77
	v_max3_f32 v197, v104, v78, v79
	ds_read_b64_tr_b16 v[152:153], v196 offset:12288
	ds_read_b64_tr_b16 v[144:145], v196 offset:12800
	ds_read_b64_tr_b16 v[120:121], v196 offset:13312
	ds_read_b64_tr_b16 v[104:105], v196 offset:13824
	ds_read_b64_tr_b16 v[154:155], v196 offset:14336
	ds_read_b64_tr_b16 v[146:147], v196 offset:14848
	ds_read_b64_tr_b16 v[122:123], v196 offset:15360
	ds_read_b64_tr_b16 v[106:107], v196 offset:15872
	v_mov_b32_e32 v196, v197
	s_nop 1
	v_permlane32_swap_b32_e32 v197, v196
	v_max_f32_e32 v196, v196, v196
	v_max_f32_e32 v197, v197, v197
	v_max_f32_e32 v196, v197, v196
	v_sub_f32_e32 v197, v196, v220
	v_cmp_ge_f32_e32 vcc, s6, v197
	s_cmp_eq_u64 vcc, exec
	v_max_f32_e32 v197, v220, v220
	s_waitcnt lgkmcnt(14)
	v_mfma_f32_32x32x16_bf16 v[0:15], v[116:119], v[234:237], v[0:15]
	s_cselect_b64 vcc, -1, 0
	v_max_f32_e32 v196, v197, v196
	v_cndmask_b32_e32 v218, v196, v220, vcc
	v_sub_f32_e32 v196, v220, v218
	v_exp_f32_e32 v196, v196
	s_nop 0
	v_cndmask_b32_e64 v220, v196, 1.0, vcc
	v_mov_b32_e32 v196, v218
	v_mfma_f32_32x32x16_bf16 v[48:63], v[116:119], v[238:241], v[48:63]
	v_sub_f32_e32 v81, v81, v196
	v_sub_f32_e32 v80, v80, v196
	v_add_f32_e64 v82, v82, -v196
	v_add_f32_e64 v83, v83, -v196
	v_add_f32_e64 v84, v84, -v196
	v_add_f32_e64 v85, v85, -v196
	v_pk_add_f32 v[86:87], v[86:87], v[196:197] op_sel_hi:[1,0] neg_lo:[0,1] neg_hi:[0,1]
	s_nop 0
	v_mfma_f32_32x32x16_bf16 v[32:47], v[116:119], v[242:245], v[32:47]
	v_add_f32_e64 v88, v88, -v196
	v_add_f32_e64 v89, v89, -v196
	v_add_f32_e64 v90, v90, -v196
	v_add_f32_e64 v91, v91, -v196
	v_add_f32_e64 v92, v92, -v196
	v_add_f32_e64 v93, v93, -v196
	v_pk_add_f32 v[94:95], v[94:95], v[196:197] op_sel_hi:[1,0] neg_lo:[0,1] neg_hi:[0,1]
	s_nop 0
	v_mfma_f32_32x32x16_bf16 v[16:31], v[116:119], v[156:159], v[16:31]
	v_sub_f32_e32 v65, v65, v196
	v_sub_f32_e32 v64, v64, v196
	v_add_f32_e64 v66, v66, -v196
	v_add_f32_e64 v67, v67, -v196
	v_add_f32_e64 v68, v68, -v196
	v_add_f32_e64 v69, v69, -v196
	v_pk_add_f32 v[70:71], v[70:71], v[196:197] op_sel_hi:[1,0] neg_lo:[0,1] neg_hi:[0,1]
	s_nop 0
	s_waitcnt lgkmcnt(11)
	v_mfma_f32_32x32x16_bf16 v[0:15], v[112:115], v[148:151], v[0:15]
	v_add_f32_e64 v72, v72, -v196
	v_add_f32_e64 v73, v73, -v196
	v_add_f32_e64 v74, v74, -v196
	v_add_f32_e64 v75, v75, -v196
	v_add_f32_e64 v76, v76, -v196
	v_add_f32_e64 v77, v77, -v196
	v_pk_add_f32 v[78:79], v[78:79], v[196:197] op_sel_hi:[1,0] neg_lo:[0,1] neg_hi:[0,1]
	s_nop 0
	s_waitcnt lgkmcnt(10)
	v_mfma_f32_32x32x16_bf16 v[48:63], v[112:115], v[124:127], v[48:63]
	v_exp_f32_e32 v80, v80
	v_exp_f32_e32 v81, v81
	v_exp_f32_e32 v82, v82
	v_exp_f32_e32 v83, v83
	s_waitcnt lgkmcnt(9)
	v_mfma_f32_32x32x16_bf16 v[32:47], v[112:115], v[108:111], v[32:47]
	v_exp_f32_e32 v84, v84
	v_exp_f32_e32 v85, v85
	v_exp_f32_e32 v86, v86
	v_exp_f32_e32 v87, v87
	s_waitcnt lgkmcnt(8)
	v_mfma_f32_32x32x16_bf16 v[16:31], v[112:115], v[100:103], v[16:31]
	v_exp_f32_e32 v88, v88
	v_exp_f32_e32 v89, v89
	v_exp_f32_e32 v90, v90
	v_exp_f32_e32 v91, v91
	s_waitcnt lgkmcnt(3)
	v_mfma_f32_32x32x16_bf16 v[0:15], v[96:99], v[152:155], v[0:15]
	v_exp_f32_e32 v92, v92
	v_exp_f32_e32 v93, v93
	v_exp_f32_e32 v94, v94
	v_exp_f32_e32 v95, v95
	s_waitcnt lgkmcnt(2)
	v_mfma_f32_32x32x16_bf16 v[48:63], v[96:99], v[144:147], v[48:63]
	v_exp_f32_e32 v64, v64
	v_exp_f32_e32 v65, v65
	v_exp_f32_e32 v66, v66
	v_exp_f32_e32 v67, v67
	v_exp_f32_e32 v68, v68
	s_waitcnt lgkmcnt(1)
	v_mfma_f32_32x32x16_bf16 v[32:47], v[96:99], v[120:123], v[32:47]
	v_exp_f32_e32 v69, v69
	v_exp_f32_e32 v70, v70
	v_exp_f32_e32 v71, v71
	v_exp_f32_e32 v72, v72
	v_exp_f32_e32 v73, v73
	s_waitcnt lgkmcnt(0)
	v_mfma_f32_32x32x16_bf16 v[16:31], v[96:99], v[104:107], v[16:31]
	v_exp_f32_e32 v74, v74
	v_exp_f32_e32 v75, v75
	v_exp_f32_e32 v76, v76
	v_exp_f32_e32 v77, v77
	v_exp_f32_e32 v78, v78
	v_exp_f32_e32 v79, v79
	v_cmp_gt_f32_e32 vcc, 1.0, v220
	s_cbranch_vccz .LBB0_230
	s_and_saveexec_b64 s[20:21], s[38:39]
	ds_write_b32 v182, v220 offset:128
	s_or_b64 exec, exec, s[20:21]
	s_waitcnt lgkmcnt(0)
	v_add_u32_e32 v108, s70, v162
	ds_read_b128 v[96:99], v108 offset:224
	ds_read_b128 v[100:103], v108 offset:192
	ds_read_b128 v[104:107], v108 offset:160
	ds_read_b128 v[108:111], v108 offset:128
	s_waitcnt lgkmcnt(3)
	v_pk_mul_f32 v[12:13], v[12:13], v[96:97]
	s_waitcnt lgkmcnt(2)
	v_pk_mul_f32 v[8:9], v[8:9], v[100:101]
	s_waitcnt lgkmcnt(1)
	v_pk_mul_f32 v[4:5], v[4:5], v[104:105]
	v_pk_mul_f32 v[14:15], v[14:15], v[98:99]
	v_pk_mul_f32 v[10:11], v[10:11], v[102:103]
	v_pk_mul_f32 v[6:7], v[6:7], v[106:107]
	s_waitcnt lgkmcnt(0)
	v_pk_mul_f32 v[2:3], v[2:3], v[110:111]
	v_pk_mul_f32 v[0:1], v[0:1], v[108:109]
	v_pk_mul_f32 v[60:61], v[60:61], v[96:97]
	v_pk_mul_f32 v[56:57], v[56:57], v[100:101]
	v_pk_mul_f32 v[52:53], v[52:53], v[104:105]
	v_pk_mul_f32 v[62:63], v[62:63], v[98:99]
	v_pk_mul_f32 v[58:59], v[58:59], v[102:103]
	v_pk_mul_f32 v[54:55], v[54:55], v[106:107]
	v_pk_mul_f32 v[50:51], v[50:51], v[110:111]
	v_pk_mul_f32 v[48:49], v[48:49], v[108:109]
	v_pk_mul_f32 v[44:45], v[44:45], v[96:97]
	v_pk_mul_f32 v[40:41], v[40:41], v[100:101]
	v_pk_mul_f32 v[36:37], v[36:37], v[104:105]
	v_pk_mul_f32 v[46:47], v[46:47], v[98:99]
	v_pk_mul_f32 v[42:43], v[42:43], v[102:103]
	v_pk_mul_f32 v[38:39], v[38:39], v[106:107]
	v_pk_mul_f32 v[34:35], v[34:35], v[110:111]
	v_pk_mul_f32 v[32:33], v[32:33], v[108:109]
	v_pk_mul_f32 v[28:29], v[28:29], v[96:97]
	v_pk_mul_f32 v[24:25], v[24:25], v[100:101]
	v_pk_mul_f32 v[20:21], v[20:21], v[104:105]
	v_pk_mul_f32 v[30:31], v[30:31], v[98:99]
	v_pk_mul_f32 v[26:27], v[26:27], v[102:103]
	v_pk_mul_f32 v[22:23], v[22:23], v[106:107]
	v_pk_mul_f32 v[18:19], v[18:19], v[110:111]
	v_pk_mul_f32 v[16:17], v[16:17], v[108:109]

.LBB0_234:
	ds_read_b128 v[96:99], v188
	ds_read_b128 v[100:103], v188 offset:8192
	ds_read_b128 v[144:147], v211
	ds_read_b128 v[148:151], v211 offset:8192
	ds_read_b128 v[152:155], v213
	ds_read_b128 v[156:159], v213 offset:8192
	ds_read_b128 v[184:187], v215
	ds_read_b128 v[210:213], v215 offset:8192
	v_add_f32_e32 v104, 0, v80
	v_add_f32_e32 v104, v81, v104
	v_add_f32_e32 v104, v82, v104
	v_add_f32_e32 v104, v83, v104
	v_add_f32_e32 v104, v84, v104
	v_add_f32_e32 v104, v85, v104
	v_add_f32_e32 v104, v86, v104
	v_add_f32_e32 v104, v87, v104
	s_nop 0
	v_add_f32_e32 v104, v88, v104
	s_waitcnt lgkmcnt(7)
	v_mfma_f32_32x32x16_bf16 v[112:127], v[96:99], v[140:143], 0
	v_add_f32_e32 v104, v89, v104
	v_add_f32_e32 v104, v90, v104
	v_add_f32_e32 v104, v91, v104
	v_add_f32_e32 v104, v92, v104
	v_add_f32_e32 v104, v93, v104
	v_add_f32_e32 v104, v94, v104
	v_add_f32_e32 v104, v95, v104
	s_nop 0
	v_add_f32_e32 v96, v64, v104
	v_add_f32_e32 v96, v65, v96
	v_add_f32_e32 v96, v66, v96
	v_add_f32_e32 v96, v67, v96
	v_add_f32_e32 v96, v68, v96
	v_add_f32_e32 v96, v69, v96
	v_add_f32_e32 v96, v70, v96
	v_add_f32_e32 v188, v71, v96
	s_waitcnt lgkmcnt(6)
	v_mfma_f32_32x32x16_bf16 v[96:111], v[100:103], v[140:143], 0
	s_nop 0
	v_add_f32_e32 v140, v72, v188
	s_waitcnt lgkmcnt(5)
	v_mfma_f32_32x32x16_bf16 v[112:127], v[144:147], v[136:139], v[112:127]
	v_add_f32_e32 v140, v73, v140
	v_add_f32_e32 v140, v74, v140
	v_add_f32_e32 v140, v75, v140
	v_add_f32_e32 v140, v76, v140
	v_add_f32_e32 v140, v77, v140
	v_add_f32_e32 v140, v78, v140
	v_add_f32_e32 v140, v79, v140
	s_nop 0
	v_mov_b32_e32 v141, v140
	s_nop 1
	v_permlane32_swap_b32_e32 v140, v141
	v_add_f32_e32 v144, v140, v141
	v_cvt_pk_bf16_f32 v214, v80, v81
	v_cvt_pk_bf16_f32 v215, v82, v83
	v_cvt_pk_bf16_f32 v216, v84, v85
	v_cvt_pk_bf16_f32 v217, v86, v87
	v_fmac_f32_e32 v144, v219, v220
	v_cvt_pk_bf16_f32 v84, v88, v89
	v_cvt_pk_bf16_f32 v85, v90, v91
	v_cvt_pk_bf16_f32 v86, v92, v93
	v_cvt_pk_bf16_f32 v87, v94, v95
	v_cvt_pk_bf16_f32 v80, v64, v65
	v_cvt_pk_bf16_f32 v81, v66, v67
	v_cvt_pk_bf16_f32 v82, v68, v69
	v_cvt_pk_bf16_f32 v83, v70, v71
	v_cvt_pk_bf16_f32 v64, v72, v73
	v_cvt_pk_bf16_f32 v65, v74, v75
	v_cvt_pk_bf16_f32 v66, v76, v77
	v_cvt_pk_bf16_f32 v67, v78, v79
	s_cmp_lg_u32 0, -1
	s_cselect_b32 s20, 0, 0
	v_add_u32_e32 v145, s20, v183
	v_add_u32_e32 v68, 0x14000, v145
	ds_read_b64_tr_b16 v[72:73], v68
	v_add_u32_e32 v68, 0x14800, v145
	s_waitcnt lgkmcnt(4)
	v_mfma_f32_32x32x16_bf16 v[112:127], v[152:155], v[132:135], v[112:127]
	ds_read_b64_tr_b16 v[74:75], v68
	v_add_u32_e32 v68, 0x14200, v145
	ds_read_b64_tr_b16 v[88:89], v68
	v_add_u32_e32 v68, 0x14a00, v145
	ds_read_b64_tr_b16 v[90:91], v68
	v_add_u32_e32 v68, 0x14400, v145
	ds_read_b64_tr_b16 v[152:153], v68
	v_mfma_f32_32x32x16_bf16 v[96:111], v[148:151], v[136:139], v[96:111]
	v_add_u32_e32 v68, 0x14c00, v145
	ds_read_b64_tr_b16 v[154:155], v68
	v_add_u32_e32 v68, 0x14600, v145
	ds_read_b64_tr_b16 v[220:221], v68
	v_add_u32_e32 v68, 0x14e00, v145
	ds_read_b64_tr_b16 v[222:223], v68
	v_add_u32_e32 v68, 0x15000, v145
	s_waitcnt lgkmcnt(9)
	v_mfma_f32_32x32x16_bf16 v[112:127], v[184:187], v[128:131], v[112:127]
	ds_read_b64_tr_b16 v[184:185], v68
	v_add_u32_e32 v68, 0x15800, v145
	ds_read_b64_tr_b16 v[186:187], v68
	v_add_u32_e32 v68, 0x15200, v145
	ds_read_b64_tr_b16 v[224:225], v68
	v_add_u32_e32 v68, 0x15a00, v145
	ds_read_b64_tr_b16 v[226:227], v68
	v_mfma_f32_32x32x16_bf16 v[96:111], v[156:159], v[132:135], v[96:111]
	v_add_u32_e32 v68, 0x15400, v145
	ds_read_b64_tr_b16 v[146:147], v68
	v_add_u32_e32 v68, 0x15c00, v145
	ds_read_b64_tr_b16 v[148:149], v68
	v_add_u32_e32 v68, 0x15600, v145
	ds_read_b64_tr_b16 v[140:141], v68
	v_add_u32_e32 v68, 0x15e00, v145
	ds_read_b64_tr_b16 v[142:143], v68
	v_add_u32_e32 v68, 0x16000, v145
	ds_read_b64_tr_b16 v[132:133], v68
	v_add_u32_e32 v68, 0x16800, v145
	ds_read_b64_tr_b16 v[134:135], v68
	v_add_u32_e32 v68, 0x16200, v145
	ds_read_b64_tr_b16 v[92:93], v68
	v_add_u32_e32 v68, 0x16a00, v145
	s_waitcnt lgkmcnt(14)
	v_mfma_f32_32x32x16_bf16 v[96:111], v[210:213], v[128:131], v[96:111]
	ds_read_b64_tr_b16 v[94:95], v68
	v_add_u32_e32 v68, 0x16400, v145
	ds_read_b64_tr_b16 v[76:77], v68
	v_add_u32_e32 v68, 0x16c00, v145
	ds_read_b64_tr_b16 v[78:79], v68
	v_add_u32_e32 v68, 0x16600, v145
	v_add_u32_e32 v70, 0x16e00, v145
	ds_read_b64_tr_b16 v[68:69], v68
	ds_read_b64_tr_b16 v[70:71], v70
	v_mfma_f32_32x32x16_bf16 v[0:15], v[214:217], v[72:75], v[0:15]
	v_max3_f32 v72, v112, v113, v114
	v_max3_f32 v72, v72, v115, v116
	v_max3_f32 v72, v72, v117, v118
	v_max3_f32 v72, v72, v119, v120
	v_mfma_f32_32x32x16_bf16 v[48:63], v[214:217], v[88:91], v[48:63]
	v_max3_f32 v72, v72, v121, v122
	v_max3_f32 v72, v72, v123, v124
	v_max3_f32 v72, v72, v125, v126
	v_max3_f32 v72, v72, v127, v96
	s_waitcnt lgkmcnt(14)
	v_mfma_f32_32x32x16_bf16 v[32:47], v[214:217], v[152:155], v[32:47]
	v_max3_f32 v72, v72, v97, v98
	v_max3_f32 v72, v72, v99, v100
	v_max3_f32 v72, v72, v101, v102
	v_max3_f32 v72, v72, v103, v104
	v_mfma_f32_32x32x16_bf16 v[16:31], v[214:217], v[220:223], v[16:31]
	v_max_f32_e32 v72, v72, v72
	v_max_f32_e32 v73, v105, v105
	v_max_f32_e32 v72, v72, v73
	v_max3_f32 v72, v72, v106, v107
	v_max3_f32 v72, v72, v108, v109
	v_max3_f32 v150, v72, v110, v111
	v_add_u32_e32 v72, 0x17000, v145
	ds_read_b64_tr_b16 v[136:137], v72
	v_add_u32_e32 v72, 0x17800, v145
	ds_read_b64_tr_b16 v[138:139], v72
	v_add_u32_e32 v72, 0x17200, v145
	ds_read_b64_tr_b16 v[128:129], v72
	v_add_u32_e32 v72, 0x17a00, v145
	ds_read_b64_tr_b16 v[130:131], v72
	v_add_u32_e32 v72, 0x17400, v145
	ds_read_b64_tr_b16 v[88:89], v72
	v_add_u32_e32 v72, 0x17c00, v145
	ds_read_b64_tr_b16 v[90:91], v72
	v_add_u32_e32 v72, 0x17600, v145
	v_add_u32_e32 v74, 0x17e00, v145
	ds_read_b64_tr_b16 v[72:73], v72
	ds_read_b64_tr_b16 v[74:75], v74
	v_mov_b32_e32 v145, v150
	s_nop 1
	v_permlane32_swap_b32_e32 v150, v145
	v_max_f32_e32 v145, v145, v145
	v_max_f32_e32 v150, v150, v150
	v_max_f32_e32 v145, v150, v145
	v_sub_f32_e32 v150, v145, v218
	v_cmp_ge_f32_e32 vcc, s6, v150
	s_cmp_eq_u64 vcc, exec
	v_max_f32_e32 v150, v218, v218
	v_mfma_f32_32x32x16_bf16 v[0:15], v[84:87], v[184:187], v[0:15]
	s_cselect_b64 vcc, -1, 0
	v_max_f32_e32 v145, v150, v145
	v_cndmask_b32_e32 v150, v145, v218, vcc
	v_sub_f32_e32 v145, v218, v150
	v_exp_f32_e32 v145, v145
	s_nop 0
	v_cndmask_b32_e64 v145, v145, 1.0, vcc
	s_waitcnt lgkmcnt(14)
	v_mfma_f32_32x32x16_bf16 v[48:63], v[84:87], v[224:227], v[48:63]
	v_sub_f32_e32 v113, v113, v150
	v_sub_f32_e32 v112, v112, v150
	v_add_f32_e64 v114, v114, -v150
	v_add_f32_e64 v115, v115, -v150
	v_add_f32_e64 v116, v116, -v150
	v_add_f32_e64 v117, v117, -v150
	v_pk_add_f32 v[118:119], v[118:119], v[150:151] op_sel_hi:[1,0] neg_lo:[0,1] neg_hi:[0,1]
	s_nop 0
	v_mfma_f32_32x32x16_bf16 v[32:47], v[84:87], v[146:149], v[32:47]
	v_add_f32_e64 v120, v120, -v150
	v_add_f32_e64 v121, v121, -v150
	v_add_f32_e64 v122, v122, -v150
	v_add_f32_e64 v123, v123, -v150
	v_add_f32_e64 v124, v124, -v150
	v_add_f32_e64 v125, v125, -v150
	v_pk_add_f32 v[126:127], v[126:127], v[150:151] op_sel_hi:[1,0] neg_lo:[0,1] neg_hi:[0,1]
	s_nop 0
	v_mfma_f32_32x32x16_bf16 v[16:31], v[84:87], v[140:143], v[16:31]
	v_sub_f32_e32 v97, v97, v150
	v_sub_f32_e32 v96, v96, v150
	v_add_f32_e64 v98, v98, -v150
	v_add_f32_e64 v99, v99, -v150
	v_add_f32_e64 v100, v100, -v150
	v_add_f32_e64 v101, v101, -v150
	v_pk_add_f32 v[102:103], v[102:103], v[150:151] op_sel_hi:[1,0] neg_lo:[0,1] neg_hi:[0,1]
	s_nop 0
	v_mfma_f32_32x32x16_bf16 v[0:15], v[80:83], v[132:135], v[0:15]
	v_add_f32_e64 v104, v104, -v150
	v_add_f32_e64 v105, v105, -v150
	v_add_f32_e64 v106, v106, -v150
	v_add_f32_e64 v107, v107, -v150
	v_add_f32_e64 v108, v108, -v150
	v_add_f32_e64 v109, v109, -v150
	v_pk_add_f32 v[110:111], v[110:111], v[150:151] op_sel_hi:[1,0] neg_lo:[0,1] neg_hi:[0,1]
	s_nop 0
	s_waitcnt lgkmcnt(12)
	v_mfma_f32_32x32x16_bf16 v[48:63], v[80:83], v[92:95], v[48:63]
	v_exp_f32_e32 v112, v112
	v_exp_f32_e32 v113, v113
	v_exp_f32_e32 v114, v114
	v_exp_f32_e32 v115, v115
	s_waitcnt lgkmcnt(10)
	v_mfma_f32_32x32x16_bf16 v[32:47], v[80:83], v[76:79], v[32:47]
	v_exp_f32_e32 v116, v116
	v_exp_f32_e32 v117, v117
	v_exp_f32_e32 v118, v118
	v_exp_f32_e32 v119, v119
	s_waitcnt lgkmcnt(8)
	v_mfma_f32_32x32x16_bf16 v[16:31], v[80:83], v[68:71], v[16:31]
	v_exp_f32_e32 v120, v120
	v_exp_f32_e32 v121, v121
	v_exp_f32_e32 v122, v122
	v_exp_f32_e32 v123, v123
	s_waitcnt lgkmcnt(6)
	v_mfma_f32_32x32x16_bf16 v[0:15], v[64:67], v[136:139], v[0:15]
	v_exp_f32_e32 v124, v124
	v_exp_f32_e32 v125, v125
	v_exp_f32_e32 v126, v126
	v_exp_f32_e32 v127, v127
	s_waitcnt lgkmcnt(4)
	v_mfma_f32_32x32x16_bf16 v[48:63], v[64:67], v[128:131], v[48:63]
	v_exp_f32_e32 v96, v96
	v_exp_f32_e32 v97, v97
	v_exp_f32_e32 v98, v98
	v_exp_f32_e32 v99, v99
	v_exp_f32_e32 v100, v100
	s_waitcnt lgkmcnt(2)
	v_mfma_f32_32x32x16_bf16 v[32:47], v[64:67], v[88:91], v[32:47]
	v_exp_f32_e32 v101, v101
	v_exp_f32_e32 v102, v102
	v_exp_f32_e32 v103, v103
	v_exp_f32_e32 v104, v104
	v_exp_f32_e32 v105, v105
	s_waitcnt lgkmcnt(0)
	v_mfma_f32_32x32x16_bf16 v[16:31], v[64:67], v[72:75], v[16:31]
	v_exp_f32_e32 v106, v106
	v_exp_f32_e32 v107, v107
	v_exp_f32_e32 v108, v108
	v_exp_f32_e32 v109, v109
	v_exp_f32_e32 v110, v110
	v_exp_f32_e32 v111, v111
	v_cmp_gt_f32_e32 vcc, 1.0, v145
	s_cbranch_vccz .LBB0_238
	s_and_saveexec_b64 s[20:21], s[38:39]
	ds_write_b32 v182, v145 offset:128
	s_or_b64 exec, exec, s[20:21]
	s_waitcnt lgkmcnt(0)
	v_add_u32_e32 v76, s70, v162
	ds_read_b128 v[64:67], v76 offset:224
	ds_read_b128 v[68:71], v76 offset:192
	ds_read_b128 v[72:75], v76 offset:160
	ds_read_b128 v[76:79], v76 offset:128
	s_waitcnt lgkmcnt(3)
	v_pk_mul_f32 v[12:13], v[12:13], v[64:65]
	s_waitcnt lgkmcnt(2)
	v_pk_mul_f32 v[8:9], v[8:9], v[68:69]
	s_waitcnt lgkmcnt(1)
	v_pk_mul_f32 v[4:5], v[4:5], v[72:73]
	v_pk_mul_f32 v[14:15], v[14:15], v[66:67]
	v_pk_mul_f32 v[10:11], v[10:11], v[70:71]
	v_pk_mul_f32 v[6:7], v[6:7], v[74:75]
	s_waitcnt lgkmcnt(0)
	v_pk_mul_f32 v[2:3], v[2:3], v[78:79]
	v_pk_mul_f32 v[0:1], v[0:1], v[76:77]
	v_pk_mul_f32 v[60:61], v[60:61], v[64:65]
	v_pk_mul_f32 v[56:57], v[56:57], v[68:69]
	v_pk_mul_f32 v[52:53], v[52:53], v[72:73]
	v_pk_mul_f32 v[62:63], v[62:63], v[66:67]
	v_pk_mul_f32 v[58:59], v[58:59], v[70:71]
	v_pk_mul_f32 v[54:55], v[54:55], v[74:75]
	v_pk_mul_f32 v[50:51], v[50:51], v[78:79]
	v_pk_mul_f32 v[48:49], v[48:49], v[76:77]
	v_pk_mul_f32 v[44:45], v[44:45], v[64:65]
	v_pk_mul_f32 v[40:41], v[40:41], v[68:69]
	v_pk_mul_f32 v[36:37], v[36:37], v[72:73]
	v_pk_mul_f32 v[46:47], v[46:47], v[66:67]
	v_pk_mul_f32 v[42:43], v[42:43], v[70:71]
	v_pk_mul_f32 v[38:39], v[38:39], v[74:75]
	v_pk_mul_f32 v[34:35], v[34:35], v[78:79]
	v_pk_mul_f32 v[32:33], v[32:33], v[76:77]
	v_pk_mul_f32 v[28:29], v[28:29], v[64:65]
	v_pk_mul_f32 v[24:25], v[24:25], v[68:69]
	v_pk_mul_f32 v[20:21], v[20:21], v[72:73]
	v_pk_mul_f32 v[30:31], v[30:31], v[66:67]
	v_pk_mul_f32 v[26:27], v[26:27], v[70:71]
	v_pk_mul_f32 v[22:23], v[22:23], v[74:75]
	v_pk_mul_f32 v[18:19], v[18:19], v[78:79]
	v_pk_mul_f32 v[16:17], v[16:17], v[76:77]
; #define SBAR() __builtin_amdgcn_sched_barrier(0)
; __device__ __forceinline__ int crow(int r, int hi) { return (r & 3) + 8 * (r >> 2) + 4 * hi; }
; __device__ __forceinline__ void attn_unit(const bf16* __restrict__ proj, bf16* __restrict__ cat, int b, int h, int qb, float lam, float oscale, const float* __restrict__ subln, const float* __restrict__ cw, char* lds) {
;     ...
;   { float ps = 0.f;
; #pragma unroll
;     for (int r = 0; r < 16; ++r) ps += pB0[r];
; #pragma unroll
;     for (int r = 0; r < 16; ++r) ps += pB1[r];
;     { auto rr = __builtin_amdgcn_permlane32_swap(__float_as_uint(ps), __float_as_uint(ps), false, false); ps = __uint_as_float(rr[0]) + __uint_as_float(rr[1]); }
;     l_reg = l_reg * alB + ps; PK4(pB0, 0, pa0); PK4(pB0, 8, pa1); PK4(pB1, 0, pa2); PK4(pB1, 8, pa3); }
;   SBAR();
;   pv_d0(o, vb0 + ((sj == 0) ? 2 : sj - 1) * SHM_V, pa0, pa1, pa2, pa3);
;   if (hi == 0) li_l[r32] = l_reg; asm volatile("s_waitcnt lgkmcnt(0)" ::: "memory");
;   float rli[16];
; #pragma unroll
;   for (int r = 0; r < 16; ++r) rli[r] = __builtin_amdgcn_rcpf(li_l[crow(r, hi)]);
;   __syncthreads();
.LBB0_238:
	v_add_f32_e32 v64, 0, v112
	v_add_f32_e32 v64, v113, v64
	v_add_f32_e32 v64, v114, v64
	v_add_f32_e32 v64, v115, v64
	v_add_f32_e32 v64, v116, v64
	v_add_f32_e32 v64, v117, v64
	v_add_f32_e32 v64, v118, v64
	v_add_f32_e32 v64, v119, v64
	v_add_f32_e32 v64, v120, v64
	v_add_f32_e32 v64, v121, v64
	v_add_f32_e32 v64, v122, v64
	v_add_f32_e32 v64, v123, v64
	v_add_f32_e32 v64, v124, v64
	v_add_f32_e32 v64, v125, v64
	v_add_f32_e32 v64, v126, v64
	v_add_f32_e32 v64, v127, v64
	v_add_f32_e32 v64, v96, v64
	v_add_f32_e32 v64, v97, v64
	v_add_f32_e32 v64, v98, v64
	v_add_f32_e32 v64, v99, v64
	v_add_f32_e32 v64, v100, v64
	v_add_f32_e32 v64, v101, v64
	v_add_f32_e32 v64, v102, v64
	v_add_f32_e32 v64, v103, v64
	v_add_f32_e32 v64, v104, v64
	v_add_f32_e32 v64, v105, v64
	v_add_f32_e32 v64, v106, v64
	v_add_f32_e32 v64, v107, v64
	v_add_f32_e32 v64, v108, v64
	v_add_f32_e32 v64, v109, v64
	v_add_f32_e32 v64, v110, v64
	s_waitcnt vmcnt(0) lgkmcnt(0)
	s_barrier
	v_add_f32_e32 v72, v111, v64
	v_mov_b32_e32 v73, v72
	s_nop 1
	v_permlane32_swap_b32_e32 v72, v73
	v_cvt_pk_bf16_f32 v74, v112, v113
	v_cvt_pk_bf16_f32 v75, v114, v115
	v_cvt_pk_bf16_f32 v76, v116, v117
	v_cvt_pk_bf16_f32 v77, v118, v119
	v_cvt_pk_bf16_f32 v78, v120, v121
	v_cvt_pk_bf16_f32 v79, v122, v123
	v_cvt_pk_bf16_f32 v80, v124, v125
	v_cvt_pk_bf16_f32 v81, v126, v127
	v_cvt_pk_bf16_f32 v68, v96, v97
	v_cvt_pk_bf16_f32 v69, v98, v99
	v_cvt_pk_bf16_f32 v70, v100, v101
	v_cvt_pk_bf16_f32 v71, v102, v103
	v_cvt_pk_bf16_f32 v64, v104, v105
	v_cvt_pk_bf16_f32 v65, v106, v107
	v_cvt_pk_bf16_f32 v66, v108, v109
	v_cvt_pk_bf16_f32 v67, v110, v111
	s_cmp_lg_u32 0, -1
	s_cselect_b32 s20, 0, 0
	v_add_u32_e32 v82, 0, v183
	v_add_u32_e32 v86, s20, v183
	ds_read_b64_tr_b16 v[82:83], v82 offset:49152
	ds_read_b64_tr_b16 v[84:85], v86 offset:51200
	s_waitcnt lgkmcnt(0)
	v_mfma_f32_32x32x16_bf16 v[0:15], v[74:77], v[82:85], v[0:15]
	ds_read_b64_tr_b16 v[84:85], v86 offset:51712
	ds_read_b64_tr_b16 v[82:83], v86 offset:49664
	s_waitcnt lgkmcnt(0)
	v_mfma_f32_32x32x16_bf16 v[48:63], v[74:77], v[82:85], v[48:63]
	ds_read_b64_tr_b16 v[82:83], v86 offset:50176
	ds_read_b64_tr_b16 v[84:85], v86 offset:52224
	s_waitcnt lgkmcnt(0)
	v_mfma_f32_32x32x16_bf16 v[32:47], v[74:77], v[82:85], v[32:47]
	ds_read_b64_tr_b16 v[82:83], v86 offset:50688
	ds_read_b64_tr_b16 v[84:85], v86 offset:52736
	s_waitcnt lgkmcnt(0)
	v_mfma_f32_32x32x16_bf16 v[16:31], v[74:77], v[82:85], v[16:31]
	ds_read_b64_tr_b16 v[74:75], v86 offset:53248
	ds_read_b64_tr_b16 v[76:77], v86 offset:55296
	s_waitcnt lgkmcnt(0)
	v_mfma_f32_32x32x16_bf16 v[0:15], v[78:81], v[74:77], v[0:15]
	ds_read_b64_tr_b16 v[76:77], v86 offset:55808
	ds_read_b64_tr_b16 v[74:75], v86 offset:53760
	s_waitcnt lgkmcnt(0)
	v_mfma_f32_32x32x16_bf16 v[48:63], v[78:81], v[74:77], v[48:63]
	ds_read_b64_tr_b16 v[74:75], v86 offset:54272
	ds_read_b64_tr_b16 v[76:77], v86 offset:56320
	s_waitcnt lgkmcnt(0)
	v_mfma_f32_32x32x16_bf16 v[32:47], v[78:81], v[74:77], v[32:47]
	ds_read_b64_tr_b16 v[74:75], v86 offset:54784
	ds_read_b64_tr_b16 v[76:77], v86 offset:56832
	s_waitcnt lgkmcnt(0)
	v_mfma_f32_32x32x16_bf16 v[16:31], v[78:81], v[74:77], v[16:31]
	ds_read_b64_tr_b16 v[74:75], v86 offset:57344
	ds_read_b64_tr_b16 v[76:77], v86 offset:59392
	s_waitcnt lgkmcnt(0)
	v_mfma_f32_32x32x16_bf16 v[0:15], v[68:71], v[74:77], v[0:15]
	ds_read_b64_tr_b16 v[76:77], v86 offset:59904
	ds_read_b64_tr_b16 v[74:75], v86 offset:57856
	s_waitcnt lgkmcnt(0)
	v_mfma_f32_32x32x16_bf16 v[48:63], v[68:71], v[74:77], v[48:63]
	ds_read_b64_tr_b16 v[74:75], v86 offset:58368
	ds_read_b64_tr_b16 v[76:77], v86 offset:60416
	s_waitcnt lgkmcnt(0)
	v_mfma_f32_32x32x16_bf16 v[32:47], v[68:71], v[74:77], v[32:47]
	ds_read_b64_tr_b16 v[74:75], v86 offset:58880
	ds_read_b64_tr_b16 v[76:77], v86 offset:60928
	s_waitcnt lgkmcnt(0)
	v_mfma_f32_32x32x16_bf16 v[16:31], v[68:71], v[74:77], v[16:31]
	ds_read_b64_tr_b16 v[68:69], v86 offset:61440
	ds_read_b64_tr_b16 v[70:71], v86 offset:63488
	s_waitcnt lgkmcnt(0)
	v_mfma_f32_32x32x16_bf16 v[0:15], v[64:67], v[68:71], v[0:15]
	ds_read_b64_tr_b16 v[70:71], v86 offset:64000
	ds_read_b64_tr_b16 v[68:69], v86 offset:61952
	s_waitcnt lgkmcnt(0)
	v_mfma_f32_32x32x16_bf16 v[48:63], v[64:67], v[68:71], v[48:63]
	ds_read_b64_tr_b16 v[68:69], v86 offset:62464
	ds_read_b64_tr_b16 v[70:71], v86 offset:64512
	s_waitcnt lgkmcnt(0)
	v_mfma_f32_32x32x16_bf16 v[32:47], v[64:67], v[68:71], v[32:47]
	ds_read_b64_tr_b16 v[68:69], v86 offset:62976
	ds_read_b64_tr_b16 v[70:71], v86 offset:65024
	s_waitcnt lgkmcnt(0)
	v_mfma_f32_32x32x16_bf16 v[16:31], v[64:67], v[68:71], v[16:31]
	s_and_saveexec_b64 s[20:21], s[38:39]
	v_add_f32_e32 v64, v72, v73
	v_fmac_f32_e32 v64, v144, v145
	ds_write_b32 v182, v64
	s_or_b64 exec, exec, s[20:21]
	s_waitcnt lgkmcnt(0)
	v_add_u32_e32 v72, s70, v162
	ds_read_b128 v[64:67], v72
	ds_read_b128 v[68:71], v72 offset:32
	s_lshl_b32 s20, s25, 14
	s_add_i32 s20, s20, 0
	s_cmp_lg_u32 s24, 1
	s_waitcnt lgkmcnt(1)
	v_rcp_f32_e32 v150, v64
	v_rcp_f32_e32 v149, v65
	v_rcp_f32_e32 v148, v66
	v_rcp_f32_e32 v147, v67
	s_waitcnt lgkmcnt(0)
	v_rcp_f32_e32 v146, v68
	ds_read_b128 v[64:67], v72 offset:64
	v_rcp_f32_e32 v145, v69
	v_rcp_f32_e32 v144, v70
	v_rcp_f32_e32 v143, v71
	ds_read_b128 v[68:71], v72 offset:96
	s_waitcnt lgkmcnt(1)
	v_rcp_f32_e32 v142, v64
	v_rcp_f32_e32 v141, v65
	v_rcp_f32_e32 v140, v66
	v_rcp_f32_e32 v139, v67
	s_waitcnt lgkmcnt(0)
	v_rcp_f32_e32 v138, v68
	v_rcp_f32_e32 v137, v69
	v_rcp_f32_e32 v135, v70
	v_rcp_f32_e32 v134, v71
	v_lshl_add_u32 v136, v177, 2, s20
	s_barrier
	s_cbranch_scc1 .LBB0_242
; __device__ __forceinline__ void attn_unit(const bf16* __restrict__ proj, bf16* __restrict__ cat, int b, int h, int qb, float lam, float oscale, const float* __restrict__ subln, const float* __restrict__ cw, char* lds) {
;     ...
;   float* X = (float*)(lds + rg * 16384);
;   if (mp == 1) {
; #pragma unroll
;     for (int d0 = 0; d0 < 4; ++d0)
; #pragma unroll
;       for (int r = 0; r < 16; ++r) X[(d0 * 16 + r) * 64 + lane] = o[d0][r] * rli[r] * lam;
;   }
	v_mul_f32_e32 v64, v0, v150
	v_mul_f32_e32 v65, v1, v149
	v_mul_f32_e32 v64, v176, v64
	v_mul_f32_e32 v65, v176, v65
	ds_write2st64_b32 v136, v64, v65 offset1:1
	v_mul_f32_e32 v64, v2, v148
	v_mul_f32_e32 v65, v3, v147
	v_mul_f32_e32 v64, v176, v64
	v_mul_f32_e32 v65, v176, v65
	ds_write2st64_b32 v136, v64, v65 offset0:2 offset1:3
	v_mul_f32_e32 v64, v4, v146
	v_mul_f32_e32 v65, v5, v145
	v_mul_f32_e32 v64, v176, v64
	v_mul_f32_e32 v65, v176, v65
	ds_write2st64_b32 v136, v64, v65 offset0:4 offset1:5
	v_mul_f32_e32 v64, v6, v144
	v_mul_f32_e32 v65, v7, v143
	v_mul_f32_e32 v64, v176, v64
	v_mul_f32_e32 v65, v176, v65
	ds_write2st64_b32 v136, v64, v65 offset0:6 offset1:7
	v_mul_f32_e32 v64, v8, v142
	v_mul_f32_e32 v65, v9, v141
	v_mul_f32_e32 v64, v176, v64
	v_mul_f32_e32 v65, v176, v65
	ds_write2st64_b32 v136, v64, v65 offset0:8 offset1:9
	v_mul_f32_e32 v64, v10, v140
	v_mul_f32_e32 v65, v11, v139
	v_mul_f32_e32 v64, v176, v64
	v_mul_f32_e32 v65, v176, v65
	ds_write2st64_b32 v136, v64, v65 offset0:10 offset1:11
	v_mul_f32_e32 v64, v12, v138
	v_mul_f32_e32 v65, v13, v137
	v_mul_f32_e32 v64, v176, v64
	v_mul_f32_e32 v65, v176, v65
	ds_write2st64_b32 v136, v64, v65 offset0:12 offset1:13
	v_mul_f32_e32 v64, v14, v135
	v_mul_f32_e32 v65, v15, v134
	v_mul_f32_e32 v64, v176, v64
	v_mul_f32_e32 v65, v176, v65
	ds_write2st64_b32 v136, v64, v65 offset0:14 offset1:15
	v_mul_f32_e32 v64, v48, v150
	v_mul_f32_e32 v65, v49, v149
	v_mul_f32_e32 v64, v176, v64
	v_mul_f32_e32 v65, v176, v65
	ds_write2st64_b32 v136, v64, v65 offset0:16 offset1:17
	v_mul_f32_e32 v64, v50, v148
	v_mul_f32_e32 v65, v51, v147
	v_mul_f32_e32 v64, v176, v64
	v_mul_f32_e32 v65, v176, v65
	ds_write2st64_b32 v136, v64, v65 offset0:18 offset1:19
	v_mul_f32_e32 v64, v52, v146
	v_mul_f32_e32 v65, v53, v145
	v_mul_f32_e32 v64, v176, v64
	v_mul_f32_e32 v65, v176, v65
	ds_write2st64_b32 v136, v64, v65 offset0:20 offset1:21
	v_mul_f32_e32 v64, v54, v144
	v_mul_f32_e32 v65, v55, v143
	v_mul_f32_e32 v64, v176, v64
	v_mul_f32_e32 v65, v176, v65
	ds_write2st64_b32 v136, v64, v65 offset0:22 offset1:23
	v_mul_f32_e32 v64, v56, v142
	v_mul_f32_e32 v65, v57, v141
	v_mul_f32_e32 v64, v176, v64
	v_mul_f32_e32 v65, v176, v65
	ds_write2st64_b32 v136, v64, v65 offset0:24 offset1:25
	v_mul_f32_e32 v64, v58, v140
	v_mul_f32_e32 v65, v59, v139
	v_mul_f32_e32 v64, v176, v64
	v_mul_f32_e32 v65, v176, v65
	ds_write2st64_b32 v136, v64, v65 offset0:26 offset1:27
	v_mul_f32_e32 v64, v60, v138
	v_mul_f32_e32 v65, v61, v137
	v_mul_f32_e32 v64, v176, v64
	v_mul_f32_e32 v65, v176, v65
	ds_write2st64_b32 v136, v64, v65 offset0:28 offset1:29
	v_mul_f32_e32 v64, v62, v135
	v_mul_f32_e32 v65, v63, v134
	v_mul_f32_e32 v64, v176, v64
	v_mul_f32_e32 v65, v176, v65
	ds_write2st64_b32 v136, v64, v65 offset0:30 offset1:31
	v_mul_f32_e32 v64, v32, v150
	v_mul_f32_e32 v65, v33, v149
	v_mul_f32_e32 v64, v176, v64
	v_mul_f32_e32 v65, v176, v65
	ds_write2st64_b32 v136, v64, v65 offset0:32 offset1:33
	v_mul_f32_e32 v64, v34, v148
	v_mul_f32_e32 v65, v35, v147
	v_mul_f32_e32 v64, v176, v64
	v_mul_f32_e32 v65, v176, v65
	ds_write2st64_b32 v136, v64, v65 offset0:34 offset1:35
	v_mul_f32_e32 v64, v36, v146
	v_mul_f32_e32 v65, v37, v145
	v_mul_f32_e32 v64, v176, v64
	v_mul_f32_e32 v65, v176, v65
	ds_write2st64_b32 v136, v64, v65 offset0:36 offset1:37
	v_mul_f32_e32 v64, v38, v144
	v_mul_f32_e32 v65, v39, v143
	v_mul_f32_e32 v64, v176, v64
	v_mul_f32_e32 v65, v176, v65
	ds_write2st64_b32 v136, v64, v65 offset0:38 offset1:39
	v_mul_f32_e32 v64, v40, v142
	v_mul_f32_e32 v65, v41, v141
	v_mul_f32_e32 v64, v176, v64
	v_mul_f32_e32 v65, v176, v65
	ds_write2st64_b32 v136, v64, v65 offset0:40 offset1:41
	v_mul_f32_e32 v64, v42, v140
	v_mul_f32_e32 v65, v43, v139
	v_mul_f32_e32 v64, v176, v64
	v_mul_f32_e32 v65, v176, v65
	ds_write2st64_b32 v136, v64, v65 offset0:42 offset1:43
	v_mul_f32_e32 v64, v44, v138
	v_mul_f32_e32 v65, v45, v137
	v_mul_f32_e32 v64, v176, v64
	v_mul_f32_e32 v65, v176, v65
	ds_write2st64_b32 v136, v64, v65 offset0:44 offset1:45
	v_mul_f32_e32 v64, v46, v135
	v_mul_f32_e32 v65, v47, v134
	v_mul_f32_e32 v64, v176, v64
	v_mul_f32_e32 v65, v176, v65
	ds_write2st64_b32 v136, v64, v65 offset0:46 offset1:47
	v_mul_f32_e32 v64, v16, v150
	v_mul_f32_e32 v65, v17, v149
	v_mul_f32_e32 v64, v176, v64
	v_mul_f32_e32 v65, v176, v65
	ds_write2st64_b32 v136, v64, v65 offset0:48 offset1:49
	v_mul_f32_e32 v64, v18, v148
	v_mul_f32_e32 v65, v19, v147
	v_mul_f32_e32 v64, v176, v64
	v_mul_f32_e32 v65, v176, v65
	ds_write2st64_b32 v136, v64, v65 offset0:50 offset1:51
	v_mul_f32_e32 v64, v20, v146
	v_mul_f32_e32 v65, v21, v145
	v_mul_f32_e32 v64, v176, v64
	v_mul_f32_e32 v65, v176, v65
	ds_write2st64_b32 v136, v64, v65 offset0:52 offset1:53
	v_mul_f32_e32 v64, v22, v144
	v_mul_f32_e32 v65, v23, v143
	v_mul_f32_e32 v64, v176, v64
	v_mul_f32_e32 v65, v176, v65
	ds_write2st64_b32 v136, v64, v65 offset0:54 offset1:55
	v_mul_f32_e32 v64, v24, v142
	v_mul_f32_e32 v65, v25, v141
	v_mul_f32_e32 v64, v176, v64
	v_mul_f32_e32 v65, v176, v65
	ds_write2st64_b32 v136, v64, v65 offset0:56 offset1:57
	v_mul_f32_e32 v64, v26, v140
	v_mul_f32_e32 v65, v27, v139
	v_mul_f32_e32 v64, v176, v64
	v_mul_f32_e32 v65, v176, v65
	ds_write2st64_b32 v136, v64, v65 offset0:58 offset1:59
	v_mul_f32_e32 v64, v28, v138
	v_mul_f32_e32 v65, v29, v137
	v_mul_f32_e32 v64, v176, v64
	v_mul_f32_e32 v65, v176, v65
	ds_write2st64_b32 v136, v64, v65 offset0:60 offset1:61
	v_mul_f32_e32 v64, v30, v135
	v_mul_f32_e32 v65, v31, v134
	v_mul_f32_e32 v64, v176, v64
	v_mul_f32_e32 v65, v176, v65
	ds_write2st64_b32 v136, v64, v65 offset0:62 offset1:63
